# final rmsnorm of the prompt rows fused into the P8 GEMM epilogue (4-workgroup partial-sum exchange through d_ws); hand-written P4b prompt scan and sample scan on LDS-DMA; P8b only normalises the sampl
# speedup vs baseline: 1.0122x; 1.0122x over previous
; __device__ __forceinline__ void hg_seq(const Frame& F, unsigned char* ws, const float* s0, float* sout, float* Og, int seq, bool sample, int vs_base, int nvs) {
;     ...
;     if (!sample) { const int b = seq >> 2; h = seq & 3; t0 = b * 2048; nch = 64; nvalid = 32; const size_t e0 = (size_t)t0 * DA + h * 128;
;         qf = ws + WS_Q + e0 * 2; vf = ws + WS_V + e0 * 2; lf = ws + WS_LOGF + e0 * 4; qp = 1024; lp = 2048; qstep = 32 * 1024; lstep = 32 * 2048; }
;     else { const int b = seq >> 2; h = seq & 3; t0 = TP + b * 8; nch = 1; nvalid = 8; const unsigned char* base = (const unsigned char*)sout + (size_t)seq * 65536;
;         qf = base; vf = base + 8192; lf = base + 16384; qp = 256; lp = 512; qstep = 0; lstep = 0; }
;     const size_t offq = (size_t)(tid >> 4) * qp + (tid & 15) * 16, offl0 = (size_t)(tid >> 5) * lp + (tid & 31) * 16, offl1 = (size_t)(16 + (tid >> 5)) * lp + (tid & 31) * 16, offl1c = tid < 160 ? offl1 : offl0;
;     {
;     f32x4 S[8];
;     if (sample && active) {
; #pragma unroll
;         for (int kb = 0; kb < 8; ++kb)
; #pragma unroll
;             for (int i = 0; i < 4; ++i) S[kb][i] = s0[((size_t)seq * 128 + 16 * kb + 4 * q + i) * 128 + 16 * vs + r];
;     } else {
; #pragma unroll
;         for (int kb = 0; kb < 8; ++kb) S[kb] = (f32x4){0.f, 0.f, 0.f, 0.f};
;     }
;     float* Ob = Og + (size_t)t0 * DA + h * 128;
;     ...
;     HgPre R0, R1, R2, R3, R4, R5;
;     R0.l1 = R0.v = (v4u){0u, 0u, 0u, 0u}; R1.l1 = R1.v = (v4u){0u, 0u, 0u, 0u}; R2.l1 = R2.v = (v4u){0u, 0u, 0u, 0u}; R3.l1 = R3.v = (v4u){0u, 0u, 0u, 0u}; R4.l1 = R4.v = (v4u){0u, 0u, 0u, 0u}; R5.l1 = R5.v = (v4u){0u, 0u, 0u, 0u};
;     HG_LOAD(R0, 0); HG_LOAD(R1, 1); HG_LOAD(R2, 2); HG_LOAD(R3, 3); HG_LOAD(R4, 4);
; __global__ void __launch_bounds__(NWAVES * 64, 2) mk_fwd(Args args) {
;     ...
;             for (int s = bid; s < NSEQ_S; s += G) hg_seq(F, ws, st_h, out + OUT_SHS, Og, s, true, 0, 8);
.LBB0_1113:
	s_and_b64 vcc, exec, s[6:7]
	s_cbranch_vccz .LBB0_1246
	s_cmpk_gt_i32 s2, 0x7f
	v_and_b32_e32 v162, 15, v189
	s_waitcnt vmcnt(3)
	v_ashrrev_i32_e32 v52, 4, v188
	v_lshlrev_b32_e32 v101, 4, v188
	v_ashrrev_i32_e32 v50, 5, v188
	v_lshrrev_b32_e32 v100, 2, v189
	v_lshlrev_b32_e32 v98, 4, v189
	v_and_b32_e32 v99, 48, v189
	s_cbranch_scc1 .LBB0_1139
	s_mov_b64 exec, -1
	s_waitcnt lgkmcnt(0)
	s_lshl_b32 s3, s2, 16
	s_add_u32 s8, s16, s3
	s_addc_u32 s9, s17, 0
	s_add_u32 s10, s20, 0x4608000
	s_addc_u32 s11, s21, 0
	s_add_u32 s10, s10, s3
	s_addc_u32 s11, s11, 0
	s_lshr_b32 s6, s2, 2
	s_lshl_b32 s6, s6, 14
	s_and_b32 s7, s2, 3
	s_lshl_b32 s7, s7, 9
	s_add_i32 s6, s6, s7
	s_add_u32 s12, s22, 0x4080000
	s_addc_u32 s13, s23, 0
	s_add_u32 s12, s12, s6
	s_addc_u32 s13, s13, 0
	s_mov_b32 s34, 0x800000
	s_mov_b32 s35, 0
	v_lshlrev_b32_e32 v142, 4, v189
	s_lshl_b32 s3, s50, 10
	v_add_u32_e32 v143, s3, v142
	v_lshrrev_b32_e32 v1, 4, v189
	v_lshlrev_b32_e32 v144, 4, v1
	s_lshl_b32 s3, s50, 4
	v_and_b32_e32 v2, 15, v189
	v_add_u32_e32 v2, s3, v2
	v_lshlrev_b32_e32 v2, 2, v2
	v_lshl_add_u32 v208, v1, 13, v2
	v_add_u32_e32 v209, 0x1000, v208
	v_lshl_add_u32 v200, v1, 11, v2
	v_add_u32_e32 v201, 0x2000, v200
	v_add_u32_e32 v202, 0x4000, v200
	v_add_u32_e32 v203, 0x6000, v200
	v_add_u32_e32 v204, 0x8000, v200
	v_add_u32_e32 v205, 0xa000, v200
	v_add_u32_e32 v206, 0xc000, v200
	v_add_u32_e32 v207, 0xe000, v200
	v_mov_b32_e32 v3, 0
	v_mov_b32_e32 v2, v143
	v_lshl_add_u64 v[210:211], s[10:11], 0, v[2:3]
	s_add_u32 s6, s10, 0x2000
	s_addc_u32 s7, s11, 0
	v_lshl_add_u64 v[212:213], s[6:7], 0, v[2:3]
	s_add_u32 s6, s10, 0x4000
	s_addc_u32 s7, s11, 0
	v_lshl_add_u64 v[214:215], s[6:7], 0, v[2:3]
	s_mov_b32 s36, 0
	s_lshl_b32 s37, s50, 10
	s_cmp_lt_u32 s50, 3
	s_cbranch_scc0 .Lsmp_p4_done
	s_movk_i32 s36, 0x6000
	s_add_i32 s37, s37, 0x6000
.Lsmp_p4_done:
	s_add_u32 s6, s10, s36
	s_addc_u32 s7, s11, 0
	v_lshl_add_u64 v[140:141], s[6:7], 0, v[2:3]
	s_lshl_b32 s38, s50, 10
	s_add_i32 s39, s38, 0x4000
	s_add_i32 s40, s38, 0x2000
	s_mov_b32 m0, s38
	s_nop 0
	global_load_lds_dwordx4 v[210:211], off
	s_mov_b32 m0, s39
	s_nop 0
	global_load_lds_dwordx4 v[212:213], off
	s_mov_b32 m0, s40
	s_nop 0
	global_load_lds_dwordx4 v[214:215], off
	s_mov_b32 m0, s37
	s_nop 0
	global_load_lds_dwordx4 v[140:141], off
	v_lshl_add_u64 v[210:211], v[210:211], 0, s[34:35]
	v_lshl_add_u64 v[212:213], v[212:213], 0, s[34:35]
	v_lshl_add_u64 v[214:215], v[214:215], 0, s[34:35]
	v_lshl_add_u64 v[140:141], v[140:141], 0, s[34:35]
	s_add_i32 m0, s38, 0x6c00
	s_nop 0
	global_load_lds_dwordx4 v[210:211], off
	s_add_i32 m0, s39, 0x6c00
	s_nop 0
	global_load_lds_dwordx4 v[212:213], off
	s_add_i32 m0, s40, 0x6c00
	s_nop 0
	global_load_lds_dwordx4 v[214:215], off
	s_add_i32 m0, s37, 0x6c00
	s_nop 0
	global_load_lds_dwordx4 v[140:141], off
	v_lshl_add_u64 v[210:211], v[210:211], 0, s[34:35]
	v_lshl_add_u64 v[212:213], v[212:213], 0, s[34:35]
	v_lshl_add_u64 v[214:215], v[214:215], 0, s[34:35]
	v_lshl_add_u64 v[140:141], v[140:141], 0, s[34:35]
	s_add_i32 m0, s38, 0xd800
	s_nop 0
	global_load_lds_dwordx4 v[210:211], off
	s_add_i32 m0, s39, 0xd800
	s_nop 0
	global_load_lds_dwordx4 v[212:213], off
	s_add_i32 m0, s40, 0xd800
	s_nop 0
	global_load_lds_dwordx4 v[214:215], off
	s_add_i32 m0, s37, 0xd800
	s_nop 0
	global_load_lds_dwordx4 v[140:141], off
	v_lshl_add_u64 v[210:211], v[210:211], 0, s[34:35]
	v_lshl_add_u64 v[212:213], v[212:213], 0, s[34:35]
	v_lshl_add_u64 v[214:215], v[214:215], 0, s[34:35]
	v_lshl_add_u64 v[140:141], v[140:141], 0, s[34:35]
	s_add_i32 m0, s38, 0x14400
	s_nop 0
	global_load_lds_dwordx4 v[210:211], off
	s_add_i32 m0, s39, 0x14400
	s_nop 0
	global_load_lds_dwordx4 v[212:213], off
	s_add_i32 m0, s40, 0x14400
	s_nop 0
	global_load_lds_dwordx4 v[214:215], off
	s_add_i32 m0, s37, 0x14400
	s_nop 0
	global_load_lds_dwordx4 v[140:141], off
	global_load_dword v4, v200, s[8:9]
	global_load_dword v5, v200, s[8:9] offset:512
	global_load_dword v6, v200, s[8:9] offset:1024
	global_load_dword v7, v200, s[8:9] offset:1536
	global_load_dword v8, v201, s[8:9]
	global_load_dword v9, v201, s[8:9] offset:512
	global_load_dword v10, v201, s[8:9] offset:1024
	global_load_dword v11, v201, s[8:9] offset:1536
	global_load_dword v12, v202, s[8:9]
	global_load_dword v13, v202, s[8:9] offset:512
	global_load_dword v14, v202, s[8:9] offset:1024
	global_load_dword v15, v202, s[8:9] offset:1536
	global_load_dword v16, v203, s[8:9]
	global_load_dword v17, v203, s[8:9] offset:512
	global_load_dword v18, v203, s[8:9] offset:1024
	global_load_dword v19, v203, s[8:9] offset:1536
	global_load_dword v20, v204, s[8:9]
	global_load_dword v21, v204, s[8:9] offset:512
	global_load_dword v22, v204, s[8:9] offset:1024
	global_load_dword v23, v204, s[8:9] offset:1536
	global_load_dword v24, v205, s[8:9]
	global_load_dword v25, v205, s[8:9] offset:512
	global_load_dword v26, v205, s[8:9] offset:1024
	global_load_dword v27, v205, s[8:9] offset:1536
	global_load_dword v28, v206, s[8:9]
	global_load_dword v29, v206, s[8:9] offset:512
	global_load_dword v30, v206, s[8:9] offset:1024
	global_load_dword v31, v206, s[8:9] offset:1536
	global_load_dword v32, v207, s[8:9]
	global_load_dword v33, v207, s[8:9] offset:512
	global_load_dword v34, v207, s[8:9] offset:1024
	global_load_dword v35, v207, s[8:9] offset:1536
	s_add_u32 s8, s8, s34
	s_addc_u32 s9, s9, 0
	global_load_dword v36, v200, s[8:9]
	global_load_dword v37, v200, s[8:9] offset:512
	global_load_dword v38, v200, s[8:9] offset:1024
	global_load_dword v39, v200, s[8:9] offset:1536
	global_load_dword v40, v201, s[8:9]
	global_load_dword v41, v201, s[8:9] offset:512
	global_load_dword v42, v201, s[8:9] offset:1024
	global_load_dword v43, v201, s[8:9] offset:1536
	global_load_dword v44, v202, s[8:9]
	global_load_dword v45, v202, s[8:9] offset:512
	global_load_dword v46, v202, s[8:9] offset:1024
	global_load_dword v47, v202, s[8:9] offset:1536
	global_load_dword v48, v203, s[8:9]
	global_load_dword v49, v203, s[8:9] offset:512
	global_load_dword v50, v203, s[8:9] offset:1024
	global_load_dword v51, v203, s[8:9] offset:1536
	global_load_dword v52, v204, s[8:9]
	global_load_dword v53, v204, s[8:9] offset:512
	global_load_dword v54, v204, s[8:9] offset:1024
	global_load_dword v55, v204, s[8:9] offset:1536
	global_load_dword v56, v205, s[8:9]
	global_load_dword v57, v205, s[8:9] offset:512
	global_load_dword v58, v205, s[8:9] offset:1024
	global_load_dword v59, v205, s[8:9] offset:1536
	global_load_dword v60, v206, s[8:9]
	global_load_dword v61, v206, s[8:9] offset:512
	global_load_dword v62, v206, s[8:9] offset:1024
	global_load_dword v63, v206, s[8:9] offset:1536
	global_load_dword v64, v207, s[8:9]
	global_load_dword v65, v207, s[8:9] offset:512
	global_load_dword v66, v207, s[8:9] offset:1024
	global_load_dword v67, v207, s[8:9] offset:1536
	s_add_u32 s8, s8, s34
	s_addc_u32 s9, s9, 0
	s_waitcnt vmcnt(32)
	s_barrier
; #define LAS __attribute__((address_space(3)))
; __device__ __forceinline__ unsigned pk2(float lo, float hi) { const f32x2_t_ v = {lo, hi}; return __builtin_bit_cast(unsigned, __builtin_convertvector(v, bf16x2_t_)); }
; __device__ __forceinline__ void hg_chunk(const LAS unsigned char* sl, f32x4 (&S)[8], float* Orow, int nvalid, int vs, int lane) {
;     const int r = lane & 15, q = lane >> 4;
;     const bf16x8 vfr = *(const LAS bf16x8*)(sl + 16384 + ((vs * 64 + lane) << 4));
;     f32x4 o0 = {0.f, 0.f, 0.f, 0.f}, o1 = {0.f, 0.f, 0.f, 0.f};
;     { const bf16x8 s0 = *(const LAS bf16x8*)(sl + 24576 + (lane << 4)), s1 = *(const LAS bf16x8*)(sl + 24576 + ((64 + lane) << 4));
;       o0 = __builtin_amdgcn_mfma_f32_16x16x32_bf16(s0, vfr, o0, 0, 0, 0); o1 = __builtin_amdgcn_mfma_f32_16x16x32_bf16(s1, vfr, o1, 0, 0, 0); }
; #pragma unroll
;     for (int m = 0; m < 4; ++m) {
;         v4u sw; sw.x = pk2(S[2 * m][0], S[2 * m][1]); sw.y = pk2(S[2 * m][2], S[2 * m][3]); sw.z = pk2(S[2 * m + 1][0], S[2 * m + 1][1]); sw.w = pk2(S[2 * m + 1][2], S[2 * m + 1][3]);
;         const bf16x8 sb = __builtin_bit_cast(bf16x8, sw);
;         const bf16x8 a0 = *(const LAS bf16x8*)(sl + ((m * 64 + lane) << 4)), a1 = *(const LAS bf16x8*)(sl + (((4 + m) * 64 + lane) << 4));
;         o0 = __builtin_amdgcn_mfma_f32_16x16x32_bf16(a0, sb, o0, 0, 0, 0); o1 = __builtin_amdgcn_mfma_f32_16x16x32_bf16(a1, sb, o1, 0, 0, 0);
;     }
; #pragma unroll
;     for (int i = 0; i < 4; ++i) { const int c0 = 4 * q + i;
;         if (c0 < nvalid) Orow[(size_t)c0 * DA + 16 * vs + r] = o0[i];
;         if (c0 + 16 < nvalid) Orow[(size_t)(c0 + 16) * DA + 16 * vs + r] = o1[i]; }
; #pragma unroll
;     for (int kb = 0; kb < 8; ++kb) { const f32x4 d = *(const LAS f32x4*)(sl + 26624 + ((16 * kb + 4 * q) << 2));
;         const bf16x8 ke = *(const LAS bf16x8*)(sl + 8192 + ((kb * 64 + lane) << 4));
;         S[kb] = __builtin_amdgcn_mfma_f32_16x16x32_bf16(ke, vfr, S[kb] * d, 0, 0, 0); }
; }
; __device__ __forceinline__ void hg_seq(const Frame& F, unsigned char* ws, const float* s0, float* sout, float* Og, int seq, bool sample, int vs_base, int nvs) {
;     ...
;     for (int kb = 0; kb < 8; ++kb)
; #pragma unroll
;         for (int i = 0; i < 4; ++i) sout[((size_t)seq * 128 + 16 * kb + 4 * q + i) * 128 + 16 * vs + r] = S[kb][i];
	v_mov_b32_e32 v1, v142
	v_mov_b32_e32 v2, v143
	v_mov_b32_e32 v3, v144
	ds_read_b128 v[164:167], v3 offset:26624
	ds_read_b128 v[168:171], v3 offset:26688
	ds_read_b128 v[172:175], v3 offset:26752
	ds_read_b128 v[176:179], v3 offset:26816
	ds_read_b128 v[180:183], v3 offset:26880
	ds_read_b128 v[184:187], v3 offset:26944
	ds_read_b128 v[148:151], v3 offset:27008
	ds_read_b128 v[152:155], v3 offset:27072
	ds_read_b128 v[84:87], v2 offset:16384
	ds_read_b128 v[88:91], v1 offset:24576
	ds_read_b128 v[92:95], v1 offset:0
	ds_read_b128 v[96:99], v1 offset:1024
	ds_read_b128 v[100:103], v1 offset:2048
	ds_read_b128 v[104:107], v1 offset:3072
	v_cvt_pk_bf16_f32 v68, v4, v5
	v_cvt_pk_bf16_f32 v69, v6, v7
	v_cvt_pk_bf16_f32 v70, v8, v9
	v_cvt_pk_bf16_f32 v71, v10, v11
	v_cvt_pk_bf16_f32 v72, v12, v13
	v_cvt_pk_bf16_f32 v73, v14, v15
	v_cvt_pk_bf16_f32 v74, v16, v17
	v_cvt_pk_bf16_f32 v75, v18, v19
	v_cvt_pk_bf16_f32 v76, v20, v21
	v_cvt_pk_bf16_f32 v77, v22, v23
	v_cvt_pk_bf16_f32 v78, v24, v25
	v_cvt_pk_bf16_f32 v79, v26, v27
	v_cvt_pk_bf16_f32 v80, v28, v29
	v_cvt_pk_bf16_f32 v81, v30, v31
	v_cvt_pk_bf16_f32 v82, v32, v33
	v_cvt_pk_bf16_f32 v83, v34, v35
	s_waitcnt lgkmcnt(6)
	v_pk_mul_f32 v[4:5], v[4:5], v[164:165]
	v_pk_mul_f32 v[6:7], v[6:7], v[166:167]
	v_pk_mul_f32 v[8:9], v[8:9], v[168:169]
	v_pk_mul_f32 v[10:11], v[10:11], v[170:171]
	v_pk_mul_f32 v[12:13], v[12:13], v[172:173]
	v_pk_mul_f32 v[14:15], v[14:15], v[174:175]
	v_pk_mul_f32 v[16:17], v[16:17], v[176:177]
	v_pk_mul_f32 v[18:19], v[18:19], v[178:179]
	v_pk_mul_f32 v[20:21], v[20:21], v[180:181]
	v_pk_mul_f32 v[22:23], v[22:23], v[182:183]
	v_pk_mul_f32 v[24:25], v[24:25], v[184:185]
	v_pk_mul_f32 v[26:27], v[26:27], v[186:187]
	v_pk_mul_f32 v[28:29], v[28:29], v[148:149]
	v_pk_mul_f32 v[30:31], v[30:31], v[150:151]
	v_pk_mul_f32 v[32:33], v[32:33], v[152:153]
	v_pk_mul_f32 v[34:35], v[34:35], v[154:155]
	ds_read_b128 v[108:111], v1 offset:8192
	ds_read_b128 v[112:115], v1 offset:9216
	ds_read_b128 v[116:119], v1 offset:10240
	ds_read_b128 v[120:123], v1 offset:11264
	ds_read_b128 v[124:127], v1 offset:12288
	ds_read_b128 v[128:131], v1 offset:13312
	ds_read_b128 v[132:135], v1 offset:14336
	ds_read_b128 v[136:139], v1 offset:15360
	s_waitcnt lgkmcnt(12)
	v_mfma_f32_16x16x32_bf16 v[196:199], v[88:91], v[84:87], 0
	s_waitcnt lgkmcnt(11)
	v_mfma_f32_16x16x32_bf16 v[196:199], v[92:95], v[68:71], v[196:199]
	s_waitcnt lgkmcnt(10)
	v_mfma_f32_16x16x32_bf16 v[196:199], v[96:99], v[72:75], v[196:199]
	s_waitcnt lgkmcnt(9)
	v_mfma_f32_16x16x32_bf16 v[196:199], v[100:103], v[76:79], v[196:199]
	s_waitcnt lgkmcnt(8)
	v_mfma_f32_16x16x32_bf16 v[196:199], v[104:107], v[80:83], v[196:199]
	s_waitcnt lgkmcnt(7)
	v_mfma_f32_16x16x32_bf16 v[4:7], v[108:111], v[84:87], v[4:7]
	s_waitcnt lgkmcnt(6)
	v_mfma_f32_16x16x32_bf16 v[8:11], v[112:115], v[84:87], v[8:11]
	s_waitcnt lgkmcnt(5)
	v_mfma_f32_16x16x32_bf16 v[12:15], v[116:119], v[84:87], v[12:15]
	s_waitcnt lgkmcnt(4)
	v_mfma_f32_16x16x32_bf16 v[16:19], v[120:123], v[84:87], v[16:19]
	s_waitcnt lgkmcnt(3)
	v_mfma_f32_16x16x32_bf16 v[20:23], v[124:127], v[84:87], v[20:23]
	s_waitcnt lgkmcnt(2)
	v_mfma_f32_16x16x32_bf16 v[24:27], v[128:131], v[84:87], v[24:27]
	s_waitcnt lgkmcnt(1)
	v_mfma_f32_16x16x32_bf16 v[28:31], v[132:135], v[84:87], v[28:31]
	s_waitcnt lgkmcnt(0)
	v_mfma_f32_16x16x32_bf16 v[32:35], v[136:139], v[84:87], v[32:35]
	s_mov_b32 exec_hi, 0
	global_store_dword v208, v196, s[12:13]
	global_store_dword v208, v197, s[12:13] offset:2048
	global_store_dword v209, v198, s[12:13]
	global_store_dword v209, v199, s[12:13] offset:2048
	s_mov_b64 exec, -1
	s_add_u32 s12, s12, 0x80000
	s_addc_u32 s13, s13, 0
	s_nop 7
	global_store_dword v200, v4, s[10:11]
	global_store_dword v200, v5, s[10:11] offset:512
	global_store_dword v200, v6, s[10:11] offset:1024
	global_store_dword v200, v7, s[10:11] offset:1536
	global_store_dword v201, v8, s[10:11]
	global_store_dword v201, v9, s[10:11] offset:512
	global_store_dword v201, v10, s[10:11] offset:1024
	global_store_dword v201, v11, s[10:11] offset:1536
	global_store_dword v202, v12, s[10:11]
	global_store_dword v202, v13, s[10:11] offset:512
	global_store_dword v202, v14, s[10:11] offset:1024
	global_store_dword v202, v15, s[10:11] offset:1536
	global_store_dword v203, v16, s[10:11]
	global_store_dword v203, v17, s[10:11] offset:512
	global_store_dword v203, v18, s[10:11] offset:1024
	global_store_dword v203, v19, s[10:11] offset:1536
	global_store_dword v204, v20, s[10:11]
	global_store_dword v204, v21, s[10:11] offset:512
	global_store_dword v204, v22, s[10:11] offset:1024
	global_store_dword v204, v23, s[10:11] offset:1536
	global_store_dword v205, v24, s[10:11]
	global_store_dword v205, v25, s[10:11] offset:512
	global_store_dword v205, v26, s[10:11] offset:1024
	global_store_dword v205, v27, s[10:11] offset:1536
	global_store_dword v206, v28, s[10:11]
	global_store_dword v206, v29, s[10:11] offset:512
	global_store_dword v206, v30, s[10:11] offset:1024
	global_store_dword v206, v31, s[10:11] offset:1536
	global_store_dword v207, v32, s[10:11]
	global_store_dword v207, v33, s[10:11] offset:512
	global_store_dword v207, v34, s[10:11] offset:1024
	global_store_dword v207, v35, s[10:11] offset:1536
	s_add_u32 s10, s10, s34
	s_addc_u32 s11, s11, 0
	s_waitcnt vmcnt(36)
; #define LAS __attribute__((address_space(3)))
; __device__ __forceinline__ unsigned pk2(float lo, float hi) { const f32x2_t_ v = {lo, hi}; return __builtin_bit_cast(unsigned, __builtin_convertvector(v, bf16x2_t_)); }
; __device__ __forceinline__ void hg_chunk(const LAS unsigned char* sl, f32x4 (&S)[8], float* Orow, int nvalid, int vs, int lane) {
;     const int r = lane & 15, q = lane >> 4;
;     const bf16x8 vfr = *(const LAS bf16x8*)(sl + 16384 + ((vs * 64 + lane) << 4));
;     f32x4 o0 = {0.f, 0.f, 0.f, 0.f}, o1 = {0.f, 0.f, 0.f, 0.f};
;     { const bf16x8 s0 = *(const LAS bf16x8*)(sl + 24576 + (lane << 4)), s1 = *(const LAS bf16x8*)(sl + 24576 + ((64 + lane) << 4));
;       o0 = __builtin_amdgcn_mfma_f32_16x16x32_bf16(s0, vfr, o0, 0, 0, 0); o1 = __builtin_amdgcn_mfma_f32_16x16x32_bf16(s1, vfr, o1, 0, 0, 0); }
; #pragma unroll
;     for (int m = 0; m < 4; ++m) {
;         v4u sw; sw.x = pk2(S[2 * m][0], S[2 * m][1]); sw.y = pk2(S[2 * m][2], S[2 * m][3]); sw.z = pk2(S[2 * m + 1][0], S[2 * m + 1][1]); sw.w = pk2(S[2 * m + 1][2], S[2 * m + 1][3]);
;         const bf16x8 sb = __builtin_bit_cast(bf16x8, sw);
;         const bf16x8 a0 = *(const LAS bf16x8*)(sl + ((m * 64 + lane) << 4)), a1 = *(const LAS bf16x8*)(sl + (((4 + m) * 64 + lane) << 4));
;         o0 = __builtin_amdgcn_mfma_f32_16x16x32_bf16(a0, sb, o0, 0, 0, 0); o1 = __builtin_amdgcn_mfma_f32_16x16x32_bf16(a1, sb, o1, 0, 0, 0);
;     }
; #pragma unroll
;     for (int i = 0; i < 4; ++i) { const int c0 = 4 * q + i;
;         if (c0 < nvalid) Orow[(size_t)c0 * DA + 16 * vs + r] = o0[i];
;         if (c0 + 16 < nvalid) Orow[(size_t)(c0 + 16) * DA + 16 * vs + r] = o1[i]; }
; #pragma unroll
;     for (int kb = 0; kb < 8; ++kb) { const f32x4 d = *(const LAS f32x4*)(sl + 26624 + ((16 * kb + 4 * q) << 2));
;         const bf16x8 ke = *(const LAS bf16x8*)(sl + 8192 + ((kb * 64 + lane) << 4));
;         S[kb] = __builtin_amdgcn_mfma_f32_16x16x32_bf16(ke, vfr, S[kb] * d, 0, 0, 0); }
; }
; __device__ __forceinline__ void hg_seq(const Frame& F, unsigned char* ws, const float* s0, float* sout, float* Og, int seq, bool sample, int vs_base, int nvs) {
;     ...
;         for (int kb = 0; kb < 8; ++kb)
; #pragma unroll
;             for (int i = 0; i < 4; ++i) S[kb][i] = s0[((size_t)seq * 128 + 16 * kb + 4 * q + i) * 128 + 16 * vs + r];
	global_load_dword v4, v200, s[8:9]
	global_load_dword v5, v200, s[8:9] offset:512
	global_load_dword v6, v200, s[8:9] offset:1024
	global_load_dword v7, v200, s[8:9] offset:1536
	global_load_dword v8, v201, s[8:9]
	global_load_dword v9, v201, s[8:9] offset:512
	global_load_dword v10, v201, s[8:9] offset:1024
	global_load_dword v11, v201, s[8:9] offset:1536
	global_load_dword v12, v202, s[8:9]
	global_load_dword v13, v202, s[8:9] offset:512
	global_load_dword v14, v202, s[8:9] offset:1024
	global_load_dword v15, v202, s[8:9] offset:1536
	global_load_dword v16, v203, s[8:9]
	global_load_dword v17, v203, s[8:9] offset:512
	global_load_dword v18, v203, s[8:9] offset:1024
	global_load_dword v19, v203, s[8:9] offset:1536
	global_load_dword v20, v204, s[8:9]
	global_load_dword v21, v204, s[8:9] offset:512
	global_load_dword v22, v204, s[8:9] offset:1024
	global_load_dword v23, v204, s[8:9] offset:1536
	global_load_dword v24, v205, s[8:9]
	global_load_dword v25, v205, s[8:9] offset:512
	global_load_dword v26, v205, s[8:9] offset:1024
	global_load_dword v27, v205, s[8:9] offset:1536
	global_load_dword v28, v206, s[8:9]
	global_load_dword v29, v206, s[8:9] offset:512
	global_load_dword v30, v206, s[8:9] offset:1024
	global_load_dword v31, v206, s[8:9] offset:1536
	global_load_dword v32, v207, s[8:9]
	global_load_dword v33, v207, s[8:9] offset:512
	global_load_dword v34, v207, s[8:9] offset:1024
	global_load_dword v35, v207, s[8:9] offset:1536
	s_add_u32 s8, s8, s34
	s_addc_u32 s9, s9, 0
	v_add_u32_e32 v1, 0x6c00, v142
	v_add_u32_e32 v2, 0x6c00, v143
	v_add_u32_e32 v3, 0x6c00, v144
	ds_read_b128 v[164:167], v3 offset:26624
	ds_read_b128 v[168:171], v3 offset:26688
	ds_read_b128 v[172:175], v3 offset:26752
	ds_read_b128 v[176:179], v3 offset:26816
	ds_read_b128 v[180:183], v3 offset:26880
	ds_read_b128 v[184:187], v3 offset:26944
	ds_read_b128 v[148:151], v3 offset:27008
	ds_read_b128 v[152:155], v3 offset:27072
	ds_read_b128 v[84:87], v2 offset:16384
	ds_read_b128 v[88:91], v1 offset:24576
	ds_read_b128 v[92:95], v1 offset:0
	ds_read_b128 v[96:99], v1 offset:1024
	ds_read_b128 v[100:103], v1 offset:2048
	ds_read_b128 v[104:107], v1 offset:3072
	v_cvt_pk_bf16_f32 v68, v36, v37
	v_cvt_pk_bf16_f32 v69, v38, v39
	v_cvt_pk_bf16_f32 v70, v40, v41
	v_cvt_pk_bf16_f32 v71, v42, v43
	v_cvt_pk_bf16_f32 v72, v44, v45
	v_cvt_pk_bf16_f32 v73, v46, v47
	v_cvt_pk_bf16_f32 v74, v48, v49
	v_cvt_pk_bf16_f32 v75, v50, v51
	v_cvt_pk_bf16_f32 v76, v52, v53
	v_cvt_pk_bf16_f32 v77, v54, v55
	v_cvt_pk_bf16_f32 v78, v56, v57
	v_cvt_pk_bf16_f32 v79, v58, v59
	v_cvt_pk_bf16_f32 v80, v60, v61
	v_cvt_pk_bf16_f32 v81, v62, v63
	v_cvt_pk_bf16_f32 v82, v64, v65
	v_cvt_pk_bf16_f32 v83, v66, v67
	s_waitcnt lgkmcnt(6)
	v_pk_mul_f32 v[36:37], v[36:37], v[164:165]
	v_pk_mul_f32 v[38:39], v[38:39], v[166:167]
	v_pk_mul_f32 v[40:41], v[40:41], v[168:169]
	v_pk_mul_f32 v[42:43], v[42:43], v[170:171]
	v_pk_mul_f32 v[44:45], v[44:45], v[172:173]
	v_pk_mul_f32 v[46:47], v[46:47], v[174:175]
	v_pk_mul_f32 v[48:49], v[48:49], v[176:177]
	v_pk_mul_f32 v[50:51], v[50:51], v[178:179]
	v_pk_mul_f32 v[52:53], v[52:53], v[180:181]
	v_pk_mul_f32 v[54:55], v[54:55], v[182:183]
	v_pk_mul_f32 v[56:57], v[56:57], v[184:185]
	v_pk_mul_f32 v[58:59], v[58:59], v[186:187]
	v_pk_mul_f32 v[60:61], v[60:61], v[148:149]
	v_pk_mul_f32 v[62:63], v[62:63], v[150:151]
	v_pk_mul_f32 v[64:65], v[64:65], v[152:153]
	v_pk_mul_f32 v[66:67], v[66:67], v[154:155]
	ds_read_b128 v[108:111], v1 offset:8192
	ds_read_b128 v[112:115], v1 offset:9216
	ds_read_b128 v[116:119], v1 offset:10240
	ds_read_b128 v[120:123], v1 offset:11264
	ds_read_b128 v[124:127], v1 offset:12288
	ds_read_b128 v[128:131], v1 offset:13312
	ds_read_b128 v[132:135], v1 offset:14336
	ds_read_b128 v[136:139], v1 offset:15360
	s_waitcnt lgkmcnt(12)
	v_mfma_f32_16x16x32_bf16 v[196:199], v[88:91], v[84:87], 0
	s_waitcnt lgkmcnt(11)
	v_mfma_f32_16x16x32_bf16 v[196:199], v[92:95], v[68:71], v[196:199]
	s_waitcnt lgkmcnt(10)
	v_mfma_f32_16x16x32_bf16 v[196:199], v[96:99], v[72:75], v[196:199]
	s_waitcnt lgkmcnt(9)
	v_mfma_f32_16x16x32_bf16 v[196:199], v[100:103], v[76:79], v[196:199]
	s_waitcnt lgkmcnt(8)
	v_mfma_f32_16x16x32_bf16 v[196:199], v[104:107], v[80:83], v[196:199]
	s_waitcnt lgkmcnt(7)
	v_mfma_f32_16x16x32_bf16 v[36:39], v[108:111], v[84:87], v[36:39]
	s_waitcnt lgkmcnt(6)
	v_mfma_f32_16x16x32_bf16 v[40:43], v[112:115], v[84:87], v[40:43]
	s_waitcnt lgkmcnt(5)
	v_mfma_f32_16x16x32_bf16 v[44:47], v[116:119], v[84:87], v[44:47]
	s_waitcnt lgkmcnt(4)
	v_mfma_f32_16x16x32_bf16 v[48:51], v[120:123], v[84:87], v[48:51]
	s_waitcnt lgkmcnt(3)
	v_mfma_f32_16x16x32_bf16 v[52:55], v[124:127], v[84:87], v[52:55]
	s_waitcnt lgkmcnt(2)
	v_mfma_f32_16x16x32_bf16 v[56:59], v[128:131], v[84:87], v[56:59]
	s_waitcnt lgkmcnt(1)
	v_mfma_f32_16x16x32_bf16 v[60:63], v[132:135], v[84:87], v[60:63]
	s_waitcnt lgkmcnt(0)
; #define LAS __attribute__((address_space(3)))
; __device__ __forceinline__ unsigned pk2(float lo, float hi) { const f32x2_t_ v = {lo, hi}; return __builtin_bit_cast(unsigned, __builtin_convertvector(v, bf16x2_t_)); }
; __device__ __forceinline__ void hg_chunk(const LAS unsigned char* sl, f32x4 (&S)[8], float* Orow, int nvalid, int vs, int lane) {
;     const int r = lane & 15, q = lane >> 4;
;     const bf16x8 vfr = *(const LAS bf16x8*)(sl + 16384 + ((vs * 64 + lane) << 4));
;     f32x4 o0 = {0.f, 0.f, 0.f, 0.f}, o1 = {0.f, 0.f, 0.f, 0.f};
;     { const bf16x8 s0 = *(const LAS bf16x8*)(sl + 24576 + (lane << 4)), s1 = *(const LAS bf16x8*)(sl + 24576 + ((64 + lane) << 4));
;       o0 = __builtin_amdgcn_mfma_f32_16x16x32_bf16(s0, vfr, o0, 0, 0, 0); o1 = __builtin_amdgcn_mfma_f32_16x16x32_bf16(s1, vfr, o1, 0, 0, 0); }
; #pragma unroll
;     for (int m = 0; m < 4; ++m) {
;         v4u sw; sw.x = pk2(S[2 * m][0], S[2 * m][1]); sw.y = pk2(S[2 * m][2], S[2 * m][3]); sw.z = pk2(S[2 * m + 1][0], S[2 * m + 1][1]); sw.w = pk2(S[2 * m + 1][2], S[2 * m + 1][3]);
;         const bf16x8 sb = __builtin_bit_cast(bf16x8, sw);
;         const bf16x8 a0 = *(const LAS bf16x8*)(sl + ((m * 64 + lane) << 4)), a1 = *(const LAS bf16x8*)(sl + (((4 + m) * 64 + lane) << 4));
;         o0 = __builtin_amdgcn_mfma_f32_16x16x32_bf16(a0, sb, o0, 0, 0, 0); o1 = __builtin_amdgcn_mfma_f32_16x16x32_bf16(a1, sb, o1, 0, 0, 0);
;     }
; #pragma unroll
;     for (int i = 0; i < 4; ++i) { const int c0 = 4 * q + i;
;         if (c0 < nvalid) Orow[(size_t)c0 * DA + 16 * vs + r] = o0[i];
;         if (c0 + 16 < nvalid) Orow[(size_t)(c0 + 16) * DA + 16 * vs + r] = o1[i]; }
; #pragma unroll
;     for (int kb = 0; kb < 8; ++kb) { const f32x4 d = *(const LAS f32x4*)(sl + 26624 + ((16 * kb + 4 * q) << 2));
;         const bf16x8 ke = *(const LAS bf16x8*)(sl + 8192 + ((kb * 64 + lane) << 4));
;         S[kb] = __builtin_amdgcn_mfma_f32_16x16x32_bf16(ke, vfr, S[kb] * d, 0, 0, 0); }
; }
; __device__ __forceinline__ void hg_seq(const Frame& F, unsigned char* ws, const float* s0, float* sout, float* Og, int seq, bool sample, int vs_base, int nvs) {
;     ...
;     for (int kb = 0; kb < 8; ++kb)
; #pragma unroll
;         for (int i = 0; i < 4; ++i) sout[((size_t)seq * 128 + 16 * kb + 4 * q + i) * 128 + 16 * vs + r] = S[kb][i];
	v_mfma_f32_16x16x32_bf16 v[64:67], v[136:139], v[84:87], v[64:67]
	s_mov_b32 exec_hi, 0
	global_store_dword v208, v196, s[12:13]
	global_store_dword v208, v197, s[12:13] offset:2048
	global_store_dword v209, v198, s[12:13]
	global_store_dword v209, v199, s[12:13] offset:2048
	s_mov_b64 exec, -1
	s_add_u32 s12, s12, 0x80000
	s_addc_u32 s13, s13, 0
	s_nop 7
	global_store_dword v200, v36, s[10:11]
	global_store_dword v200, v37, s[10:11] offset:512
	global_store_dword v200, v38, s[10:11] offset:1024
	global_store_dword v200, v39, s[10:11] offset:1536
	global_store_dword v201, v40, s[10:11]
	global_store_dword v201, v41, s[10:11] offset:512
	global_store_dword v201, v42, s[10:11] offset:1024
	global_store_dword v201, v43, s[10:11] offset:1536
	global_store_dword v202, v44, s[10:11]
	global_store_dword v202, v45, s[10:11] offset:512
	global_store_dword v202, v46, s[10:11] offset:1024
	global_store_dword v202, v47, s[10:11] offset:1536
	global_store_dword v203, v48, s[10:11]
	global_store_dword v203, v49, s[10:11] offset:512
	global_store_dword v203, v50, s[10:11] offset:1024
	global_store_dword v203, v51, s[10:11] offset:1536
	global_store_dword v204, v52, s[10:11]
	global_store_dword v204, v53, s[10:11] offset:512
	global_store_dword v204, v54, s[10:11] offset:1024
	global_store_dword v204, v55, s[10:11] offset:1536
	global_store_dword v205, v56, s[10:11]
	global_store_dword v205, v57, s[10:11] offset:512
	global_store_dword v205, v58, s[10:11] offset:1024
	global_store_dword v205, v59, s[10:11] offset:1536
	global_store_dword v206, v60, s[10:11]
	global_store_dword v206, v61, s[10:11] offset:512
	global_store_dword v206, v62, s[10:11] offset:1024
	global_store_dword v206, v63, s[10:11] offset:1536
	global_store_dword v207, v64, s[10:11]
	global_store_dword v207, v65, s[10:11] offset:512
	global_store_dword v207, v66, s[10:11] offset:1024
	global_store_dword v207, v67, s[10:11] offset:1536
	s_add_u32 s10, s10, s34
	s_addc_u32 s11, s11, 0
	s_waitcnt vmcnt(36)
	global_load_dword v36, v200, s[8:9]
	global_load_dword v37, v200, s[8:9] offset:512
	global_load_dword v38, v200, s[8:9] offset:1024
	global_load_dword v39, v200, s[8:9] offset:1536
	global_load_dword v40, v201, s[8:9]
	global_load_dword v41, v201, s[8:9] offset:512
	global_load_dword v42, v201, s[8:9] offset:1024
	global_load_dword v43, v201, s[8:9] offset:1536
	global_load_dword v44, v202, s[8:9]
	global_load_dword v45, v202, s[8:9] offset:512
	global_load_dword v46, v202, s[8:9] offset:1024
	global_load_dword v47, v202, s[8:9] offset:1536
	global_load_dword v48, v203, s[8:9]
	global_load_dword v49, v203, s[8:9] offset:512
	global_load_dword v50, v203, s[8:9] offset:1024
	global_load_dword v51, v203, s[8:9] offset:1536
	global_load_dword v52, v204, s[8:9]
	global_load_dword v53, v204, s[8:9] offset:512
	global_load_dword v54, v204, s[8:9] offset:1024
	global_load_dword v55, v204, s[8:9] offset:1536
	global_load_dword v56, v205, s[8:9]
	global_load_dword v57, v205, s[8:9] offset:512
	global_load_dword v58, v205, s[8:9] offset:1024
	global_load_dword v59, v205, s[8:9] offset:1536
	global_load_dword v60, v206, s[8:9]
	global_load_dword v61, v206, s[8:9] offset:512
	global_load_dword v62, v206, s[8:9] offset:1024
	global_load_dword v63, v206, s[8:9] offset:1536
	global_load_dword v64, v207, s[8:9]
	global_load_dword v65, v207, s[8:9] offset:512
	global_load_dword v66, v207, s[8:9] offset:1024
	global_load_dword v67, v207, s[8:9] offset:1536
	s_add_u32 s8, s8, s34
	s_addc_u32 s9, s9, 0
	v_add_u32_e32 v1, 0xd800, v142
	v_add_u32_e32 v2, 0xd800, v143
	v_add_u32_e32 v3, 0xd800, v144
	ds_read_b128 v[164:167], v3 offset:26624
	ds_read_b128 v[168:171], v3 offset:26688
	ds_read_b128 v[172:175], v3 offset:26752
	ds_read_b128 v[176:179], v3 offset:26816
	ds_read_b128 v[180:183], v3 offset:26880
	ds_read_b128 v[184:187], v3 offset:26944
	ds_read_b128 v[148:151], v3 offset:27008
	ds_read_b128 v[152:155], v3 offset:27072
	ds_read_b128 v[84:87], v2 offset:16384
	ds_read_b128 v[88:91], v1 offset:24576
	ds_read_b128 v[92:95], v1 offset:0
	ds_read_b128 v[96:99], v1 offset:1024
	ds_read_b128 v[100:103], v1 offset:2048
	ds_read_b128 v[104:107], v1 offset:3072
	v_cvt_pk_bf16_f32 v68, v4, v5
	v_cvt_pk_bf16_f32 v69, v6, v7
	v_cvt_pk_bf16_f32 v70, v8, v9
	v_cvt_pk_bf16_f32 v71, v10, v11
	v_cvt_pk_bf16_f32 v72, v12, v13
	v_cvt_pk_bf16_f32 v73, v14, v15
	v_cvt_pk_bf16_f32 v74, v16, v17
	v_cvt_pk_bf16_f32 v75, v18, v19
	v_cvt_pk_bf16_f32 v76, v20, v21
	v_cvt_pk_bf16_f32 v77, v22, v23
	v_cvt_pk_bf16_f32 v78, v24, v25
	v_cvt_pk_bf16_f32 v79, v26, v27
	v_cvt_pk_bf16_f32 v80, v28, v29
	v_cvt_pk_bf16_f32 v81, v30, v31
	v_cvt_pk_bf16_f32 v82, v32, v33
	v_cvt_pk_bf16_f32 v83, v34, v35
	s_waitcnt lgkmcnt(6)
	v_pk_mul_f32 v[4:5], v[4:5], v[164:165]
	v_pk_mul_f32 v[6:7], v[6:7], v[166:167]
	v_pk_mul_f32 v[8:9], v[8:9], v[168:169]
	v_pk_mul_f32 v[10:11], v[10:11], v[170:171]
	v_pk_mul_f32 v[12:13], v[12:13], v[172:173]
	v_pk_mul_f32 v[14:15], v[14:15], v[174:175]
	v_pk_mul_f32 v[16:17], v[16:17], v[176:177]
	v_pk_mul_f32 v[18:19], v[18:19], v[178:179]
	v_pk_mul_f32 v[20:21], v[20:21], v[180:181]
	v_pk_mul_f32 v[22:23], v[22:23], v[182:183]
	v_pk_mul_f32 v[24:25], v[24:25], v[184:185]
	v_pk_mul_f32 v[26:27], v[26:27], v[186:187]
	v_pk_mul_f32 v[28:29], v[28:29], v[148:149]
	v_pk_mul_f32 v[30:31], v[30:31], v[150:151]
	v_pk_mul_f32 v[32:33], v[32:33], v[152:153]
	v_pk_mul_f32 v[34:35], v[34:35], v[154:155]
	ds_read_b128 v[108:111], v1 offset:8192
	ds_read_b128 v[112:115], v1 offset:9216
	ds_read_b128 v[116:119], v1 offset:10240
	ds_read_b128 v[120:123], v1 offset:11264
	ds_read_b128 v[124:127], v1 offset:12288
	ds_read_b128 v[128:131], v1 offset:13312
	ds_read_b128 v[132:135], v1 offset:14336
	ds_read_b128 v[136:139], v1 offset:15360
	s_waitcnt lgkmcnt(12)
; #define LAS __attribute__((address_space(3)))
; __device__ __forceinline__ unsigned pk2(float lo, float hi) { const f32x2_t_ v = {lo, hi}; return __builtin_bit_cast(unsigned, __builtin_convertvector(v, bf16x2_t_)); }
; __device__ __forceinline__ void hg_chunk(const LAS unsigned char* sl, f32x4 (&S)[8], float* Orow, int nvalid, int vs, int lane) {
;     const int r = lane & 15, q = lane >> 4;
;     const bf16x8 vfr = *(const LAS bf16x8*)(sl + 16384 + ((vs * 64 + lane) << 4));
;     f32x4 o0 = {0.f, 0.f, 0.f, 0.f}, o1 = {0.f, 0.f, 0.f, 0.f};
;     { const bf16x8 s0 = *(const LAS bf16x8*)(sl + 24576 + (lane << 4)), s1 = *(const LAS bf16x8*)(sl + 24576 + ((64 + lane) << 4));
;       o0 = __builtin_amdgcn_mfma_f32_16x16x32_bf16(s0, vfr, o0, 0, 0, 0); o1 = __builtin_amdgcn_mfma_f32_16x16x32_bf16(s1, vfr, o1, 0, 0, 0); }
; #pragma unroll
;     for (int m = 0; m < 4; ++m) {
;         v4u sw; sw.x = pk2(S[2 * m][0], S[2 * m][1]); sw.y = pk2(S[2 * m][2], S[2 * m][3]); sw.z = pk2(S[2 * m + 1][0], S[2 * m + 1][1]); sw.w = pk2(S[2 * m + 1][2], S[2 * m + 1][3]);
;         const bf16x8 sb = __builtin_bit_cast(bf16x8, sw);
;         const bf16x8 a0 = *(const LAS bf16x8*)(sl + ((m * 64 + lane) << 4)), a1 = *(const LAS bf16x8*)(sl + (((4 + m) * 64 + lane) << 4));
;         o0 = __builtin_amdgcn_mfma_f32_16x16x32_bf16(a0, sb, o0, 0, 0, 0); o1 = __builtin_amdgcn_mfma_f32_16x16x32_bf16(a1, sb, o1, 0, 0, 0);
;     }
; #pragma unroll
;     for (int i = 0; i < 4; ++i) { const int c0 = 4 * q + i;
;         if (c0 < nvalid) Orow[(size_t)c0 * DA + 16 * vs + r] = o0[i];
;         if (c0 + 16 < nvalid) Orow[(size_t)(c0 + 16) * DA + 16 * vs + r] = o1[i]; }
; #pragma unroll
;     for (int kb = 0; kb < 8; ++kb) { const f32x4 d = *(const LAS f32x4*)(sl + 26624 + ((16 * kb + 4 * q) << 2));
;         const bf16x8 ke = *(const LAS bf16x8*)(sl + 8192 + ((kb * 64 + lane) << 4));
;         S[kb] = __builtin_amdgcn_mfma_f32_16x16x32_bf16(ke, vfr, S[kb] * d, 0, 0, 0); }
; }
; __device__ __forceinline__ void hg_seq(const Frame& F, unsigned char* ws, const float* s0, float* sout, float* Og, int seq, bool sample, int vs_base, int nvs) {
;     ...
;     for (int kb = 0; kb < 8; ++kb)
; #pragma unroll
;         for (int i = 0; i < 4; ++i) sout[((size_t)seq * 128 + 16 * kb + 4 * q + i) * 128 + 16 * vs + r] = S[kb][i];
	v_mfma_f32_16x16x32_bf16 v[196:199], v[88:91], v[84:87], 0
	s_waitcnt lgkmcnt(11)
	v_mfma_f32_16x16x32_bf16 v[196:199], v[92:95], v[68:71], v[196:199]
	s_waitcnt lgkmcnt(10)
	v_mfma_f32_16x16x32_bf16 v[196:199], v[96:99], v[72:75], v[196:199]
	s_waitcnt lgkmcnt(9)
	v_mfma_f32_16x16x32_bf16 v[196:199], v[100:103], v[76:79], v[196:199]
	s_waitcnt lgkmcnt(8)
	v_mfma_f32_16x16x32_bf16 v[196:199], v[104:107], v[80:83], v[196:199]
	s_waitcnt lgkmcnt(7)
	v_mfma_f32_16x16x32_bf16 v[4:7], v[108:111], v[84:87], v[4:7]
	s_waitcnt lgkmcnt(6)
	v_mfma_f32_16x16x32_bf16 v[8:11], v[112:115], v[84:87], v[8:11]
	s_waitcnt lgkmcnt(5)
	v_mfma_f32_16x16x32_bf16 v[12:15], v[116:119], v[84:87], v[12:15]
	s_waitcnt lgkmcnt(4)
	v_mfma_f32_16x16x32_bf16 v[16:19], v[120:123], v[84:87], v[16:19]
	s_waitcnt lgkmcnt(3)
	v_mfma_f32_16x16x32_bf16 v[20:23], v[124:127], v[84:87], v[20:23]
	s_waitcnt lgkmcnt(2)
	v_mfma_f32_16x16x32_bf16 v[24:27], v[128:131], v[84:87], v[24:27]
	s_waitcnt lgkmcnt(1)
	v_mfma_f32_16x16x32_bf16 v[28:31], v[132:135], v[84:87], v[28:31]
	s_waitcnt lgkmcnt(0)
	v_mfma_f32_16x16x32_bf16 v[32:35], v[136:139], v[84:87], v[32:35]
	s_mov_b32 exec_hi, 0
	global_store_dword v208, v196, s[12:13]
	global_store_dword v208, v197, s[12:13] offset:2048
	global_store_dword v209, v198, s[12:13]
	global_store_dword v209, v199, s[12:13] offset:2048
	s_mov_b64 exec, -1
	s_add_u32 s12, s12, 0x80000
	s_addc_u32 s13, s13, 0
	s_nop 7
	global_store_dword v200, v4, s[10:11]
	global_store_dword v200, v5, s[10:11] offset:512
	global_store_dword v200, v6, s[10:11] offset:1024
	global_store_dword v200, v7, s[10:11] offset:1536
	global_store_dword v201, v8, s[10:11]
	global_store_dword v201, v9, s[10:11] offset:512
	global_store_dword v201, v10, s[10:11] offset:1024
	global_store_dword v201, v11, s[10:11] offset:1536
	global_store_dword v202, v12, s[10:11]
	global_store_dword v202, v13, s[10:11] offset:512
	global_store_dword v202, v14, s[10:11] offset:1024
	global_store_dword v202, v15, s[10:11] offset:1536
	global_store_dword v203, v16, s[10:11]
	global_store_dword v203, v17, s[10:11] offset:512
	global_store_dword v203, v18, s[10:11] offset:1024
	global_store_dword v203, v19, s[10:11] offset:1536
	global_store_dword v204, v20, s[10:11]
	global_store_dword v204, v21, s[10:11] offset:512
	global_store_dword v204, v22, s[10:11] offset:1024
	global_store_dword v204, v23, s[10:11] offset:1536
	global_store_dword v205, v24, s[10:11]
	global_store_dword v205, v25, s[10:11] offset:512
	global_store_dword v205, v26, s[10:11] offset:1024
	global_store_dword v205, v27, s[10:11] offset:1536
	global_store_dword v206, v28, s[10:11]
	global_store_dword v206, v29, s[10:11] offset:512
	global_store_dword v206, v30, s[10:11] offset:1024
	global_store_dword v206, v31, s[10:11] offset:1536
	global_store_dword v207, v32, s[10:11]
	global_store_dword v207, v33, s[10:11] offset:512
	global_store_dword v207, v34, s[10:11] offset:1024
	global_store_dword v207, v35, s[10:11] offset:1536
	s_add_u32 s10, s10, s34
	s_addc_u32 s11, s11, 0
	s_waitcnt vmcnt(36)
	v_add_u32_e32 v1, 0x14400, v142
	v_add_u32_e32 v2, 0x14400, v143
	v_add_u32_e32 v3, 0x14400, v144
	ds_read_b128 v[164:167], v3 offset:26624
	ds_read_b128 v[168:171], v3 offset:26688
	ds_read_b128 v[172:175], v3 offset:26752
	ds_read_b128 v[176:179], v3 offset:26816
	ds_read_b128 v[180:183], v3 offset:26880
	ds_read_b128 v[184:187], v3 offset:26944
	ds_read_b128 v[148:151], v3 offset:27008
	ds_read_b128 v[152:155], v3 offset:27072
	ds_read_b128 v[84:87], v2 offset:16384
	ds_read_b128 v[88:91], v1 offset:24576
	ds_read_b128 v[92:95], v1 offset:0
	ds_read_b128 v[96:99], v1 offset:1024
	ds_read_b128 v[100:103], v1 offset:2048
	ds_read_b128 v[104:107], v1 offset:3072
	v_cvt_pk_bf16_f32 v68, v36, v37
	v_cvt_pk_bf16_f32 v69, v38, v39
	v_cvt_pk_bf16_f32 v70, v40, v41
	v_cvt_pk_bf16_f32 v71, v42, v43
	v_cvt_pk_bf16_f32 v72, v44, v45
	v_cvt_pk_bf16_f32 v73, v46, v47
	v_cvt_pk_bf16_f32 v74, v48, v49
	v_cvt_pk_bf16_f32 v75, v50, v51
	v_cvt_pk_bf16_f32 v76, v52, v53
	v_cvt_pk_bf16_f32 v77, v54, v55
	v_cvt_pk_bf16_f32 v78, v56, v57
	v_cvt_pk_bf16_f32 v79, v58, v59
	v_cvt_pk_bf16_f32 v80, v60, v61
	v_cvt_pk_bf16_f32 v81, v62, v63
	v_cvt_pk_bf16_f32 v82, v64, v65
	v_cvt_pk_bf16_f32 v83, v66, v67
	s_waitcnt lgkmcnt(6)
; #define LAS __attribute__((address_space(3)))
; #define LDSBAR() do { asm volatile("s_waitcnt lgkmcnt(0)" ::: "memory"); __builtin_amdgcn_s_barrier(); asm volatile("" ::: "memory"); } while (0)
; __device__ __forceinline__ void hg_chunk(const LAS unsigned char* sl, f32x4 (&S)[8], float* Orow, int nvalid, int vs, int lane) {
;     const int r = lane & 15, q = lane >> 4;
;     const bf16x8 vfr = *(const LAS bf16x8*)(sl + 16384 + ((vs * 64 + lane) << 4));
;     f32x4 o0 = {0.f, 0.f, 0.f, 0.f}, o1 = {0.f, 0.f, 0.f, 0.f};
;     { const bf16x8 s0 = *(const LAS bf16x8*)(sl + 24576 + (lane << 4)), s1 = *(const LAS bf16x8*)(sl + 24576 + ((64 + lane) << 4));
;       o0 = __builtin_amdgcn_mfma_f32_16x16x32_bf16(s0, vfr, o0, 0, 0, 0); o1 = __builtin_amdgcn_mfma_f32_16x16x32_bf16(s1, vfr, o1, 0, 0, 0); }
; #pragma unroll
;     for (int m = 0; m < 4; ++m) {
;         v4u sw; sw.x = pk2(S[2 * m][0], S[2 * m][1]); sw.y = pk2(S[2 * m][2], S[2 * m][3]); sw.z = pk2(S[2 * m + 1][0], S[2 * m + 1][1]); sw.w = pk2(S[2 * m + 1][2], S[2 * m + 1][3]);
;         const bf16x8 sb = __builtin_bit_cast(bf16x8, sw);
;         const bf16x8 a0 = *(const LAS bf16x8*)(sl + ((m * 64 + lane) << 4)), a1 = *(const LAS bf16x8*)(sl + (((4 + m) * 64 + lane) << 4));
;         o0 = __builtin_amdgcn_mfma_f32_16x16x32_bf16(a0, sb, o0, 0, 0, 0); o1 = __builtin_amdgcn_mfma_f32_16x16x32_bf16(a1, sb, o1, 0, 0, 0);
;     }
; #pragma unroll
;     for (int i = 0; i < 4; ++i) { const int c0 = 4 * q + i;
;         if (c0 < nvalid) Orow[(size_t)c0 * DA + 16 * vs + r] = o0[i];
;         if (c0 + 16 < nvalid) Orow[(size_t)(c0 + 16) * DA + 16 * vs + r] = o1[i]; }
; #pragma unroll
;     for (int kb = 0; kb < 8; ++kb) { const f32x4 d = *(const LAS f32x4*)(sl + 26624 + ((16 * kb + 4 * q) << 2));
;         const bf16x8 ke = *(const LAS bf16x8*)(sl + 8192 + ((kb * 64 + lane) << 4));
;         S[kb] = __builtin_amdgcn_mfma_f32_16x16x32_bf16(ke, vfr, S[kb] * d, 0, 0, 0); }
; }
; __device__ __forceinline__ void hg_seq(const Frame& F, unsigned char* ws, const float* s0, float* sout, float* Og, int seq, bool sample, int vs_base, int nvs) {
;     ...
;     for (int kb = 0; kb < 8; ++kb)
; #pragma unroll
;         for (int i = 0; i < 4; ++i) sout[((size_t)seq * 128 + 16 * kb + 4 * q + i) * 128 + 16 * vs + r] = S[kb][i];
;     }
;     LDSBAR();
	v_pk_mul_f32 v[36:37], v[36:37], v[164:165]
	v_pk_mul_f32 v[38:39], v[38:39], v[166:167]
	v_pk_mul_f32 v[40:41], v[40:41], v[168:169]
	v_pk_mul_f32 v[42:43], v[42:43], v[170:171]
	v_pk_mul_f32 v[44:45], v[44:45], v[172:173]
	v_pk_mul_f32 v[46:47], v[46:47], v[174:175]
	v_pk_mul_f32 v[48:49], v[48:49], v[176:177]
	v_pk_mul_f32 v[50:51], v[50:51], v[178:179]
	v_pk_mul_f32 v[52:53], v[52:53], v[180:181]
	v_pk_mul_f32 v[54:55], v[54:55], v[182:183]
	v_pk_mul_f32 v[56:57], v[56:57], v[184:185]
	v_pk_mul_f32 v[58:59], v[58:59], v[186:187]
	v_pk_mul_f32 v[60:61], v[60:61], v[148:149]
	v_pk_mul_f32 v[62:63], v[62:63], v[150:151]
	v_pk_mul_f32 v[64:65], v[64:65], v[152:153]
	v_pk_mul_f32 v[66:67], v[66:67], v[154:155]
	ds_read_b128 v[108:111], v1 offset:8192
	ds_read_b128 v[112:115], v1 offset:9216
	ds_read_b128 v[116:119], v1 offset:10240
	ds_read_b128 v[120:123], v1 offset:11264
	ds_read_b128 v[124:127], v1 offset:12288
	ds_read_b128 v[128:131], v1 offset:13312
	ds_read_b128 v[132:135], v1 offset:14336
	ds_read_b128 v[136:139], v1 offset:15360
	s_waitcnt lgkmcnt(12)
	v_mfma_f32_16x16x32_bf16 v[196:199], v[88:91], v[84:87], 0
	s_waitcnt lgkmcnt(11)
	v_mfma_f32_16x16x32_bf16 v[196:199], v[92:95], v[68:71], v[196:199]
	s_waitcnt lgkmcnt(10)
	v_mfma_f32_16x16x32_bf16 v[196:199], v[96:99], v[72:75], v[196:199]
	s_waitcnt lgkmcnt(9)
	v_mfma_f32_16x16x32_bf16 v[196:199], v[100:103], v[76:79], v[196:199]
	s_waitcnt lgkmcnt(8)
	v_mfma_f32_16x16x32_bf16 v[196:199], v[104:107], v[80:83], v[196:199]
	s_waitcnt lgkmcnt(7)
	v_mfma_f32_16x16x32_bf16 v[36:39], v[108:111], v[84:87], v[36:39]
	s_waitcnt lgkmcnt(6)
	v_mfma_f32_16x16x32_bf16 v[40:43], v[112:115], v[84:87], v[40:43]
	s_waitcnt lgkmcnt(5)
	v_mfma_f32_16x16x32_bf16 v[44:47], v[116:119], v[84:87], v[44:47]
	s_waitcnt lgkmcnt(4)
	v_mfma_f32_16x16x32_bf16 v[48:51], v[120:123], v[84:87], v[48:51]
	s_waitcnt lgkmcnt(3)
	v_mfma_f32_16x16x32_bf16 v[52:55], v[124:127], v[84:87], v[52:55]
	s_waitcnt lgkmcnt(2)
	v_mfma_f32_16x16x32_bf16 v[56:59], v[128:131], v[84:87], v[56:59]
	s_waitcnt lgkmcnt(1)
	v_mfma_f32_16x16x32_bf16 v[60:63], v[132:135], v[84:87], v[60:63]
	s_waitcnt lgkmcnt(0)
	v_mfma_f32_16x16x32_bf16 v[64:67], v[136:139], v[84:87], v[64:67]
	s_mov_b32 exec_hi, 0
	global_store_dword v208, v196, s[12:13]
	global_store_dword v208, v197, s[12:13] offset:2048
	global_store_dword v209, v198, s[12:13]
	global_store_dword v209, v199, s[12:13] offset:2048
	s_mov_b64 exec, -1
	s_add_u32 s12, s12, 0x80000
	s_addc_u32 s13, s13, 0
	s_nop 7
	global_store_dword v200, v36, s[10:11]
	global_store_dword v200, v37, s[10:11] offset:512
	global_store_dword v200, v38, s[10:11] offset:1024
	global_store_dword v200, v39, s[10:11] offset:1536
	global_store_dword v201, v40, s[10:11]
	global_store_dword v201, v41, s[10:11] offset:512
	global_store_dword v201, v42, s[10:11] offset:1024
	global_store_dword v201, v43, s[10:11] offset:1536
	global_store_dword v202, v44, s[10:11]
	global_store_dword v202, v45, s[10:11] offset:512
	global_store_dword v202, v46, s[10:11] offset:1024
	global_store_dword v202, v47, s[10:11] offset:1536
	global_store_dword v203, v48, s[10:11]
	global_store_dword v203, v49, s[10:11] offset:512
	global_store_dword v203, v50, s[10:11] offset:1024
	global_store_dword v203, v51, s[10:11] offset:1536
	global_store_dword v204, v52, s[10:11]
	global_store_dword v204, v53, s[10:11] offset:512
	global_store_dword v204, v54, s[10:11] offset:1024
	global_store_dword v204, v55, s[10:11] offset:1536
	global_store_dword v205, v56, s[10:11]
	global_store_dword v205, v57, s[10:11] offset:512
	global_store_dword v205, v58, s[10:11] offset:1024
	global_store_dword v205, v59, s[10:11] offset:1536
	global_store_dword v206, v60, s[10:11]
	global_store_dword v206, v61, s[10:11] offset:512
	global_store_dword v206, v62, s[10:11] offset:1024
	global_store_dword v206, v63, s[10:11] offset:1536
	global_store_dword v207, v64, s[10:11]
	global_store_dword v207, v65, s[10:11] offset:512
	global_store_dword v207, v66, s[10:11] offset:1024
	global_store_dword v207, v67, s[10:11] offset:1536
	s_add_u32 s10, s10, s34
	s_addc_u32 s11, s11, 0
	s_waitcnt lgkmcnt(0)
	s_barrier

; #define LAS __attribute__((address_space(3)))
; __device__ __forceinline__ void hg_chunk(const LAS unsigned char* sl, f32x4 (&S)[8], float* Orow, int nvalid, int vs, int lane) {
;     const int r = lane & 15, q = lane >> 4;
;     const bf16x8 vfr = *(const LAS bf16x8*)(sl + 16384 + ((vs * 64 + lane) << 4));
;     f32x4 o0 = {0.f, 0.f, 0.f, 0.f}, o1 = {0.f, 0.f, 0.f, 0.f};
;     { const bf16x8 s0 = *(const LAS bf16x8*)(sl + 24576 + (lane << 4)), s1 = *(const LAS bf16x8*)(sl + 24576 + ((64 + lane) << 4));
;       o0 = __builtin_amdgcn_mfma_f32_16x16x32_bf16(s0, vfr, o0, 0, 0, 0); o1 = __builtin_amdgcn_mfma_f32_16x16x32_bf16(s1, vfr, o1, 0, 0, 0); }
; #pragma unroll
;     for (int m = 0; m < 4; ++m) {
;         v4u sw; sw.x = pk2(S[2 * m][0], S[2 * m][1]); sw.y = pk2(S[2 * m][2], S[2 * m][3]); sw.z = pk2(S[2 * m + 1][0], S[2 * m + 1][1]); sw.w = pk2(S[2 * m + 1][2], S[2 * m + 1][3]);
;         const bf16x8 sb = __builtin_bit_cast(bf16x8, sw);
;         const bf16x8 a0 = *(const LAS bf16x8*)(sl + ((m * 64 + lane) << 4)), a1 = *(const LAS bf16x8*)(sl + (((4 + m) * 64 + lane) << 4));
;         o0 = __builtin_amdgcn_mfma_f32_16x16x32_bf16(a0, sb, o0, 0, 0, 0); o1 = __builtin_amdgcn_mfma_f32_16x16x32_bf16(a1, sb, o1, 0, 0, 0);
;     }
; #pragma unroll
;     for (int i = 0; i < 4; ++i) { const int c0 = 4 * q + i;
;         if (c0 < nvalid) Orow[(size_t)c0 * DA + 16 * vs + r] = o0[i];
;         if (c0 + 16 < nvalid) Orow[(size_t)(c0 + 16) * DA + 16 * vs + r] = o1[i]; }
; #pragma unroll
;     for (int kb = 0; kb < 8; ++kb) { const f32x4 d = *(const LAS f32x4*)(sl + 26624 + ((16 * kb + 4 * q) << 2));
;         const bf16x8 ke = *(const LAS bf16x8*)(sl + 8192 + ((kb * 64 + lane) << 4));
;         S[kb] = __builtin_amdgcn_mfma_f32_16x16x32_bf16(ke, vfr, S[kb] * d, 0, 0, 0); }
; }
; __device__ __forceinline__ void hg_seq(const Frame& F, unsigned char* ws, const float* s0, float* sout, float* Og, int seq, bool sample, int vs_base, int nvs) {
;     ...
;     for (int n = 0; n < nch; n += 6) {
;         HG_LOAD(R5, n + 5); if (active) hg_chunk(ring, S, Ob + (size_t)(n + 0) * 32 * DA, nvalid, vs, lane); if (n + 1 < nch) HG_STORE(R1, 1); LDSBAR(); if (n + 1 >= nch) break;
;         HG_LOAD(R0, n + 6); if (active) hg_chunk(ring + HG_SLOT, S, Ob + (size_t)(n + 1) * 32 * DA, nvalid, vs, lane); if (n + 2 < nch) HG_STORE(R2, 0); LDSBAR(); if (n + 2 >= nch) break;
.LBB0_1194:
	s_and_b64 vcc, exec, s[6:7]
	s_cbranch_vccz .LBB0_1246
	s_mov_b64 exec, -1
	s_lshr_b32 s6, s2, 4
	s_bfe_u32 s7, s2, 0x20002
	s_and_b32 s8, s2, 3
	s_lshl_b32 s8, s8, 1
	s_lshl_b32 s9, s6, 21
	s_lshl_b32 s3, s7, 8
	s_add_u32 s9, s9, s3
	s_add_u32 s10, s22, s9
	s_addc_u32 s11, s23, 0
	s_lshl_b32 s9, s9, 1
	s_add_u32 s12, s22, s9
	s_addc_u32 s13, s23, 0
	s_add_u32 s14, s10, 0xb980000
	s_addc_u32 s15, s11, 0
	s_add_u32 s16, s10, 0xca80000
	s_addc_u32 s17, s11, 0
	s_add_u32 s34, s12, 0xdb80000
	s_addc_u32 s35, s13, 0
	s_add_u32 s36, s12, 0x2080000
	s_addc_u32 s37, s13, 0
	s_mov_b32 s62, 0
	s_cmp_lt_u32 s50, 2
	s_cbranch_scc0 .Lscan_loader
	v_lshlrev_b32_e32 v160, 4, v189
	s_lshl_b32 s3, s50, 10
	v_add_u32_e32 v161, s3, v160
	v_lshrrev_b32_e32 v1, 4, v189
	v_lshlrev_b32_e32 v163, 4, v1
	s_add_i32 s3, s8, s50
	s_lshl_b32 s3, s3, 4
	v_and_b32_e32 v2, 15, v189
	v_add_u32_e32 v2, s3, v2
	v_lshlrev_b32_e32 v2, 2, v2
	v_lshl_add_u32 v172, v1, 13, v2
	v_add_u32_e32 v173, 0x1000, v172
	v_add_u32_e32 v174, 0x8000, v172
	v_add_u32_e32 v175, 0x9000, v172
	v_lshl_add_u32 v176, v1, 11, v2
	v_mov_b32_e32 v4, 0
	v_mov_b32_e32 v5, 0
	v_mov_b32_e32 v6, 0
	v_mov_b32_e32 v7, 0
	v_mov_b32_e32 v8, 0
	v_mov_b32_e32 v9, 0
	v_mov_b32_e32 v10, 0
	v_mov_b32_e32 v11, 0
	v_mov_b32_e32 v12, 0
	v_mov_b32_e32 v13, 0
	v_mov_b32_e32 v14, 0
	v_mov_b32_e32 v15, 0
	v_mov_b32_e32 v16, 0
	v_mov_b32_e32 v17, 0
	v_mov_b32_e32 v18, 0
	v_mov_b32_e32 v19, 0
	v_mov_b32_e32 v20, 0
	v_mov_b32_e32 v21, 0
	v_mov_b32_e32 v22, 0
	v_mov_b32_e32 v23, 0
	v_mov_b32_e32 v24, 0
	v_mov_b32_e32 v25, 0
	v_mov_b32_e32 v26, 0
	v_mov_b32_e32 v27, 0
	v_mov_b32_e32 v28, 0
	v_mov_b32_e32 v29, 0
	v_mov_b32_e32 v30, 0
	v_mov_b32_e32 v31, 0
	v_mov_b32_e32 v32, 0
	v_mov_b32_e32 v33, 0
	v_mov_b32_e32 v34, 0
	v_mov_b32_e32 v35, 0
	s_mov_b32 s60, 0
	s_barrier
.Lscan_act_loop:
	v_add_u32_e32 v1, s60, v160
	v_add_u32_e32 v2, s60, v161
	v_add_u32_e32 v3, s60, v163
	ds_read_b128 v[128:131], v3 offset:20480
	ds_read_b128 v[132:135], v3 offset:20544
	ds_read_b128 v[136:139], v3 offset:20608
	ds_read_b128 v[140:143], v3 offset:20672
	ds_read_b128 v[144:147], v3 offset:20736
	ds_read_b128 v[148:151], v3 offset:20800
	ds_read_b128 v[152:155], v3 offset:20864
	ds_read_b128 v[156:159], v3 offset:20928
	ds_read_b128 v[52:55], v2 offset:16384
	ds_read_b128 v[56:59], v1 offset:18432
	ds_read_b128 v[60:63], v1 offset:19456
	ds_read_b128 v[64:67], v1 offset:0
	ds_read_b128 v[80:83], v1 offset:4096
	ds_read_b128 v[68:71], v1 offset:1024
	ds_read_b128 v[84:87], v1 offset:5120
	v_cvt_pk_bf16_f32 v36, v4, v5
	v_cvt_pk_bf16_f32 v37, v6, v7
	v_cvt_pk_bf16_f32 v38, v8, v9
	v_cvt_pk_bf16_f32 v39, v10, v11
	v_cvt_pk_bf16_f32 v40, v12, v13
	v_cvt_pk_bf16_f32 v41, v14, v15
	v_cvt_pk_bf16_f32 v42, v16, v17
	v_cvt_pk_bf16_f32 v43, v18, v19
	v_cvt_pk_bf16_f32 v44, v20, v21
	v_cvt_pk_bf16_f32 v45, v22, v23
	v_cvt_pk_bf16_f32 v46, v24, v25
	v_cvt_pk_bf16_f32 v47, v26, v27
	v_cvt_pk_bf16_f32 v48, v28, v29
	v_cvt_pk_bf16_f32 v49, v30, v31
	v_cvt_pk_bf16_f32 v50, v32, v33
	v_cvt_pk_bf16_f32 v51, v34, v35
	s_waitcnt lgkmcnt(7)
	v_pk_mul_f32 v[4:5], v[4:5], v[128:129]
	v_pk_mul_f32 v[6:7], v[6:7], v[130:131]
	v_pk_mul_f32 v[8:9], v[8:9], v[132:133]
	v_pk_mul_f32 v[10:11], v[10:11], v[134:135]
	v_pk_mul_f32 v[12:13], v[12:13], v[136:137]
	v_pk_mul_f32 v[14:15], v[14:15], v[138:139]
	v_pk_mul_f32 v[16:17], v[16:17], v[140:141]
	v_pk_mul_f32 v[18:19], v[18:19], v[142:143]
	v_pk_mul_f32 v[20:21], v[20:21], v[144:145]
	v_pk_mul_f32 v[22:23], v[22:23], v[146:147]
	v_pk_mul_f32 v[24:25], v[24:25], v[148:149]
	v_pk_mul_f32 v[26:27], v[26:27], v[150:151]
	v_pk_mul_f32 v[28:29], v[28:29], v[152:153]
	v_pk_mul_f32 v[30:31], v[30:31], v[154:155]
	v_pk_mul_f32 v[32:33], v[32:33], v[156:157]
	v_pk_mul_f32 v[34:35], v[34:35], v[158:159]
	ds_read_b128 v[72:75], v1 offset:2048
	ds_read_b128 v[88:91], v1 offset:6144
	ds_read_b128 v[76:79], v1 offset:3072
	ds_read_b128 v[92:95], v1 offset:7168
	ds_read_b128 v[96:99], v1 offset:8192
	ds_read_b128 v[100:103], v1 offset:9216
	ds_read_b128 v[104:107], v1 offset:10240
	ds_read_b128 v[108:111], v1 offset:11264
	ds_read_b128 v[112:115], v1 offset:12288
	ds_read_b128 v[116:119], v1 offset:13312
	ds_read_b128 v[120:123], v1 offset:14336
	ds_read_b128 v[124:127], v1 offset:15360
	s_waitcnt lgkmcnt(15)
	v_mfma_f32_16x16x32_bf16 v[164:167], v[56:59], v[52:55], 0
	v_mfma_f32_16x16x32_bf16 v[168:171], v[60:63], v[52:55], 0
	v_mfma_f32_16x16x32_bf16 v[164:167], v[64:67], v[36:39], v[164:167]
	s_waitcnt lgkmcnt(14)
	v_mfma_f32_16x16x32_bf16 v[168:171], v[80:83], v[36:39], v[168:171]
	s_waitcnt lgkmcnt(13)
	v_mfma_f32_16x16x32_bf16 v[164:167], v[68:71], v[40:43], v[164:167]
	s_waitcnt lgkmcnt(12)
	v_mfma_f32_16x16x32_bf16 v[168:171], v[84:87], v[40:43], v[168:171]
	s_waitcnt lgkmcnt(11)
	v_mfma_f32_16x16x32_bf16 v[164:167], v[72:75], v[44:47], v[164:167]
	s_waitcnt lgkmcnt(10)
	v_mfma_f32_16x16x32_bf16 v[168:171], v[88:91], v[44:47], v[168:171]
	s_waitcnt lgkmcnt(9)
	v_mfma_f32_16x16x32_bf16 v[164:167], v[76:79], v[48:51], v[164:167]
	s_waitcnt lgkmcnt(8)
	v_mfma_f32_16x16x32_bf16 v[168:171], v[92:95], v[48:51], v[168:171]
	s_waitcnt lgkmcnt(7)
	v_mfma_f32_16x16x32_bf16 v[4:7], v[96:99], v[52:55], v[4:7]
	s_waitcnt lgkmcnt(6)
	v_mfma_f32_16x16x32_bf16 v[8:11], v[100:103], v[52:55], v[8:11]
	s_waitcnt lgkmcnt(5)
	v_mfma_f32_16x16x32_bf16 v[12:15], v[104:107], v[52:55], v[12:15]
	s_waitcnt lgkmcnt(4)
	v_mfma_f32_16x16x32_bf16 v[16:19], v[108:111], v[52:55], v[16:19]
	s_waitcnt lgkmcnt(3)
	v_mfma_f32_16x16x32_bf16 v[20:23], v[112:115], v[52:55], v[20:23]
	s_waitcnt lgkmcnt(2)
	v_mfma_f32_16x16x32_bf16 v[24:27], v[116:119], v[52:55], v[24:27]
	s_waitcnt lgkmcnt(1)
	v_mfma_f32_16x16x32_bf16 v[28:31], v[120:123], v[52:55], v[28:31]
	s_waitcnt lgkmcnt(0)
	v_mfma_f32_16x16x32_bf16 v[32:35], v[124:127], v[52:55], v[32:35]
	global_store_dword v172, v164, s[36:37]
	global_store_dword v172, v165, s[36:37] offset:2048
	global_store_dword v173, v166, s[36:37]
	global_store_dword v173, v167, s[36:37] offset:2048
	global_store_dword v174, v168, s[36:37]
	global_store_dword v174, v169, s[36:37] offset:2048
	global_store_dword v175, v170, s[36:37]
	global_store_dword v175, v171, s[36:37] offset:2048
	s_add_u32 s36, s36, 0x10000
	s_addc_u32 s37, s37, 0
	s_add_i32 s60, s60, 21504
	s_cmp_lt_u32 s60, 129024
	s_cselect_b32 s60, s60, 0
	s_add_i32 s62, s62, 1
	s_waitcnt lgkmcnt(0)
	s_barrier
; __device__ __forceinline__ void hg_seq(const Frame& F, unsigned char* ws, const float* s0, float* sout, float* Og, int seq, bool sample, int vs_base, int nvs) {
;     ...
;     if (active) {
; #pragma unroll
;     for (int kb = 0; kb < 8; ++kb)
; #pragma unroll
;         for (int i = 0; i < 4; ++i) sout[((size_t)seq * 128 + 16 * kb + 4 * q + i) * 128 + 16 * vs + r] = S[kb][i];
;     }
	s_cmp_lt_u32 s62, 64
	s_cbranch_scc1 .Lscan_act_loop
	s_nop 7
	s_lshr_b32 s3, s2, 2
	s_lshl_b32 s3, s3, 16
	s_add_u32 s6, s20, 0x4400000
	s_addc_u32 s7, s21, 0
	s_add_u32 s6, s6, s3
	s_addc_u32 s7, s7, 0
	global_store_dword v176, v4, s[6:7]
	global_store_dword v176, v5, s[6:7] offset:512
	global_store_dword v176, v6, s[6:7] offset:1024
	global_store_dword v176, v7, s[6:7] offset:1536
	v_add_u32_e32 v176, 0x2000, v176
	global_store_dword v176, v8, s[6:7]
	global_store_dword v176, v9, s[6:7] offset:512
	global_store_dword v176, v10, s[6:7] offset:1024
	global_store_dword v176, v11, s[6:7] offset:1536
	v_add_u32_e32 v176, 0x2000, v176
	global_store_dword v176, v12, s[6:7]
	global_store_dword v176, v13, s[6:7] offset:512
	global_store_dword v176, v14, s[6:7] offset:1024
	global_store_dword v176, v15, s[6:7] offset:1536
	v_add_u32_e32 v176, 0x2000, v176
	global_store_dword v176, v16, s[6:7]
	global_store_dword v176, v17, s[6:7] offset:512
	global_store_dword v176, v18, s[6:7] offset:1024
	global_store_dword v176, v19, s[6:7] offset:1536
	v_add_u32_e32 v176, 0x2000, v176
	global_store_dword v176, v20, s[6:7]
	global_store_dword v176, v21, s[6:7] offset:512
	global_store_dword v176, v22, s[6:7] offset:1024
	global_store_dword v176, v23, s[6:7] offset:1536
	v_add_u32_e32 v176, 0x2000, v176
	global_store_dword v176, v24, s[6:7]
	global_store_dword v176, v25, s[6:7] offset:512
	global_store_dword v176, v26, s[6:7] offset:1024
	global_store_dword v176, v27, s[6:7] offset:1536
	v_add_u32_e32 v176, 0x2000, v176
	global_store_dword v176, v28, s[6:7]
	global_store_dword v176, v29, s[6:7] offset:512
	global_store_dword v176, v30, s[6:7] offset:1024
	global_store_dword v176, v31, s[6:7] offset:1536
	v_add_u32_e32 v176, 0x2000, v176
	global_store_dword v176, v32, s[6:7]
	global_store_dword v176, v33, s[6:7] offset:512
	global_store_dword v176, v34, s[6:7] offset:1024
	global_store_dword v176, v35, s[6:7] offset:1536
	s_branch .Lscan_join
.Lscan_loader:
	v_and_b32_e32 v1, 48, v189
	v_lshlrev_b32_e32 v1, 6, v1
	v_and_b32_e32 v2, 15, v189
	v_lshl_or_b32 v4, v2, 4, v1
	v_mov_b32_e32 v5, 0
	v_and_b32_e32 v1, 32, v189
	v_lshlrev_b32_e32 v1, 6, v1
	v_and_b32_e32 v2, 31, v189
	v_lshl_or_b32 v6, v2, 4, v1
	v_mov_b32_e32 v7, 0
	s_cmp_eq_u32 s50, 2
	s_cbranch_scc0 .Lscan_ld_w2_skip
	s_add_u32 s38, s14, 0
	s_addc_u32 s39, s15, 0
	v_lshl_add_u64 v[8:9], s[38:39], 0, v[4:5]
	s_movk_i32 s46, 0x0
	s_mov_b32 s52, 0x8000
	s_mov_b32 s53, 0
	s_add_u32 s38, s14, 4096
	s_addc_u32 s39, s15, 0
	v_lshl_add_u64 v[10:11], s[38:39], 0, v[4:5]
	s_movk_i32 s47, 0x400
	s_mov_b32 s54, 0x8000
	s_mov_b32 s55, 0
	s_add_u32 s38, s14, 8192
	s_addc_u32 s39, s15, 0
	v_lshl_add_u64 v[12:13], s[38:39], 0, v[4:5]
	s_movk_i32 s48, 0x800
	s_mov_b32 s56, 0x8000
	s_mov_b32 s57, 0
	s_add_u32 s38, s14, 12288
	s_addc_u32 s39, s15, 0
	v_lshl_add_u64 v[14:15], s[38:39], 0, v[4:5]
	s_movk_i32 s49, 0xc00
	s_mov_b32 s58, 0x8000
	s_mov_b32 s59, 0
	s_branch .Lscan_ld_go
.Lscan_ld_w2_skip:
	s_cmp_eq_u32 s50, 3
	s_cbranch_scc0 .Lscan_ld_w3_skip
	s_add_u32 s38, s14, 16384
	s_addc_u32 s39, s15, 0
	v_lshl_add_u64 v[8:9], s[38:39], 0, v[4:5]
	s_movk_i32 s46, 0x1000
	s_mov_b32 s52, 0x8000
	s_mov_b32 s53, 0
	s_add_u32 s38, s14, 20480
	s_addc_u32 s39, s15, 0
	v_lshl_add_u64 v[10:11], s[38:39], 0, v[4:5]
	s_movk_i32 s47, 0x1400
	s_mov_b32 s54, 0x8000
	s_mov_b32 s55, 0
	s_add_u32 s38, s14, 24576
	s_addc_u32 s39, s15, 0
	v_lshl_add_u64 v[12:13], s[38:39], 0, v[4:5]
	s_movk_i32 s48, 0x1800
	s_mov_b32 s56, 0x8000
	s_mov_b32 s57, 0
	s_add_u32 s38, s14, 28672
	s_addc_u32 s39, s15, 0
	v_lshl_add_u64 v[14:15], s[38:39], 0, v[4:5]
	s_movk_i32 s49, 0x1c00
	s_mov_b32 s58, 0x8000
	s_mov_b32 s59, 0
	s_branch .Lscan_ld_go
; __device__ __forceinline__ void hg_seq(const Frame& F, unsigned char* ws, const float* s0, float* sout, float* Og, int seq, bool sample, int vs_base, int nvs) {
;     ...
;     HgPre R0, R1, R2, R3, R4, R5;
;     R0.l1 = R0.v = (v4u){0u, 0u, 0u, 0u}; R1.l1 = R1.v = (v4u){0u, 0u, 0u, 0u}; R2.l1 = R2.v = (v4u){0u, 0u, 0u, 0u}; R3.l1 = R3.v = (v4u){0u, 0u, 0u, 0u}; R4.l1 = R4.v = (v4u){0u, 0u, 0u, 0u}; R5.l1 = R5.v = (v4u){0u, 0u, 0u, 0u};
;     HG_LOAD(R0, 0); HG_LOAD(R1, 1); HG_LOAD(R2, 2); HG_LOAD(R3, 3); HG_LOAD(R4, 4);
.Lscan_ld_w3_skip:
	s_cmp_eq_u32 s50, 4
	s_cbranch_scc0 .Lscan_ld_w4_skip
	s_add_u32 s38, s34, 0
	s_addc_u32 s39, s35, 0
	v_lshl_add_u64 v[8:9], s[38:39], 0, v[6:7]
	s_movk_i32 s46, 0x2000
	s_mov_b32 s52, 0x10000
	s_mov_b32 s53, 0
	s_add_u32 s38, s34, 4096
	s_addc_u32 s39, s35, 0
	v_lshl_add_u64 v[10:11], s[38:39], 0, v[6:7]
	s_movk_i32 s47, 0x2400
	s_mov_b32 s54, 0x10000
	s_mov_b32 s55, 0
	s_add_u32 s38, s34, 8192
	s_addc_u32 s39, s35, 0
	v_lshl_add_u64 v[12:13], s[38:39], 0, v[6:7]
	s_movk_i32 s48, 0x2800
	s_mov_b32 s56, 0x10000
	s_mov_b32 s57, 0
	s_add_u32 s38, s34, 12288
	s_addc_u32 s39, s35, 0
	v_lshl_add_u64 v[14:15], s[38:39], 0, v[6:7]
	s_movk_i32 s49, 0x2c00
	s_mov_b32 s58, 0x10000
	s_mov_b32 s59, 0
	s_branch .Lscan_ld_go
.Lscan_ld_w4_skip:
	s_cmp_eq_u32 s50, 5
	s_cbranch_scc0 .Lscan_ld_w5_skip
	s_add_u32 s38, s34, 16384
	s_addc_u32 s39, s35, 0
	v_lshl_add_u64 v[8:9], s[38:39], 0, v[6:7]
	s_movk_i32 s46, 0x3000
	s_mov_b32 s52, 0x10000
	s_mov_b32 s53, 0
	s_add_u32 s38, s34, 20480
	s_addc_u32 s39, s35, 0
	v_lshl_add_u64 v[10:11], s[38:39], 0, v[6:7]
	s_movk_i32 s47, 0x3400
	s_mov_b32 s54, 0x10000
	s_mov_b32 s55, 0
	s_add_u32 s38, s34, 24576
	s_addc_u32 s39, s35, 0
	v_lshl_add_u64 v[12:13], s[38:39], 0, v[6:7]
	s_movk_i32 s48, 0x3800
	s_mov_b32 s56, 0x10000
	s_mov_b32 s57, 0
	s_add_u32 s38, s34, 28672
	s_addc_u32 s39, s35, 0
	v_lshl_add_u64 v[14:15], s[38:39], 0, v[6:7]
	s_movk_i32 s49, 0x3c00
	s_mov_b32 s58, 0x10000
	s_mov_b32 s59, 0
	s_branch .Lscan_ld_go
.Lscan_ld_w5_skip:
	s_cmp_eq_u32 s50, 6
	s_cbranch_scc0 .Lscan_ld_w6_skip
	s_lshl_b32 s3, s8, 12
	s_add_u32 s38, s16, s3
	s_addc_u32 s39, s17, 0
	v_lshl_add_u64 v[8:9], s[38:39], 0, v[4:5]
	s_movk_i32 s46, 0x4000
	s_mov_b32 s52, 0x8000
	s_mov_b32 s53, 0
	s_lshl_b32 s3, s8, 12
	s_add_i32 s3, s3, 0x1000
	s_add_u32 s38, s16, s3
	s_addc_u32 s39, s17, 0
	v_lshl_add_u64 v[10:11], s[38:39], 0, v[4:5]
	s_movk_i32 s47, 0x4400
	s_mov_b32 s54, 0x8000
	s_mov_b32 s55, 0
	s_add_u32 s38, s34, 32768
	s_addc_u32 s39, s35, 0
	v_lshl_add_u64 v[12:13], s[38:39], 0, v[6:7]
	s_movk_i32 s48, 0x4800
	s_mov_b32 s56, 0x10000
	s_mov_b32 s57, 0
	s_add_u32 s38, s34, 36864
	s_addc_u32 s39, s35, 0
	v_lshl_add_u64 v[14:15], s[38:39], 0, v[6:7]
	s_movk_i32 s49, 0x4c00
	s_mov_b32 s58, 0x10000
	s_mov_b32 s59, 0
	s_branch .Lscan_ld_go
.Lscan_ld_w6_skip:
	s_cmp_eq_u32 s50, 7
	s_cbranch_scc0 .Lscan_ld_w7_skip
	s_add_u32 s38, s34, 40960
	s_addc_u32 s39, s35, 0
	v_lshl_add_u64 v[8:9], s[38:39], 0, v[6:7]
	s_movk_i32 s46, 0x5000
	s_mov_b32 s52, 0x10000
	s_mov_b32 s53, 0
	s_add_u32 s38, s34, 40960
	s_addc_u32 s39, s35, 0
	v_lshl_add_u64 v[10:11], s[38:39], 0, v[6:7]
	s_movk_i32 s47, 0x5000
	s_mov_b32 s54, 0x10000
	s_mov_b32 s55, 0
	s_add_u32 s38, s34, 40960
	s_addc_u32 s39, s35, 0
	v_lshl_add_u64 v[12:13], s[38:39], 0, v[6:7]
	s_movk_i32 s48, 0x5000
	s_mov_b32 s56, 0x10000
	s_mov_b32 s57, 0
	s_add_u32 s38, s34, 40960
	s_addc_u32 s39, s35, 0
	v_lshl_add_u64 v[14:15], s[38:39], 0, v[6:7]
	s_movk_i32 s49, 0x5000
	s_mov_b32 s58, 0x10000
	s_mov_b32 s59, 0
	s_branch .Lscan_ld_go
.Lscan_ld_w7_skip:
.Lscan_ld_go:
	s_mov_b32 s60, 0
	s_mov_b32 s61, 0
	s_add_i32 m0, s60, s46
	s_nop 0
	global_load_lds_dwordx4 v[8:9], off
	s_add_i32 m0, s60, s47
	s_nop 0
	global_load_lds_dwordx4 v[10:11], off
	s_add_i32 m0, s60, s48
	s_nop 0
	global_load_lds_dwordx4 v[12:13], off
	s_add_i32 m0, s60, s49
	s_nop 0
	global_load_lds_dwordx4 v[14:15], off
	s_cmp_lt_u32 s61, 63
	s_cbranch_scc0 .Lscan_noadv_435
	v_lshl_add_u64 v[8:9], v[8:9], 0, s[52:53]
	v_lshl_add_u64 v[10:11], v[10:11], 0, s[54:55]
	v_lshl_add_u64 v[12:13], v[12:13], 0, s[56:57]
	v_lshl_add_u64 v[14:15], v[14:15], 0, s[58:59]
	s_add_i32 s61, s61, 1
.Lscan_noadv_435:
	s_add_i32 s60, s60, 21504
	s_cmp_lt_u32 s60, 129024
	s_cselect_b32 s60, s60, 0
	s_add_i32 m0, s60, s46
	s_nop 0
	global_load_lds_dwordx4 v[8:9], off
	s_add_i32 m0, s60, s47
	s_nop 0
	global_load_lds_dwordx4 v[10:11], off
	s_add_i32 m0, s60, s48
	s_nop 0
	global_load_lds_dwordx4 v[12:13], off
	s_add_i32 m0, s60, s49
	s_nop 0
	global_load_lds_dwordx4 v[14:15], off
	s_cmp_lt_u32 s61, 63
	s_cbranch_scc0 .Lscan_noadv_458
	v_lshl_add_u64 v[8:9], v[8:9], 0, s[52:53]
	v_lshl_add_u64 v[10:11], v[10:11], 0, s[54:55]
	v_lshl_add_u64 v[12:13], v[12:13], 0, s[56:57]
	v_lshl_add_u64 v[14:15], v[14:15], 0, s[58:59]
	s_add_i32 s61, s61, 1

; #define LDSBAR() do { asm volatile("s_waitcnt lgkmcnt(0)" ::: "memory"); __builtin_amdgcn_s_barrier(); asm volatile("" ::: "memory"); } while (0)
; #define HG_STORE(R, s) do { LAS unsigned char* d_ = ring + (s) * HG_SLOT; *(LAS v4u*)(d_ + 16 * tid) = R.q; if (vload) *(LAS v4u*)(d_ + 16384 + 16 * tid) = R.v; *(LAS v4u*)(d_ + 8192 + 16 * tid) = R.l0; \
;         if (tid < 160) *(LAS v4u*)(d_ + 24576 + 16 * tid) = R.l1; } while (0)
; __device__ __forceinline__ void hg_seq(const Frame& F, unsigned char* ws, const float* s0, float* sout, float* Og, int seq, bool sample, int vs_base, int nvs) {
;     ...
;     HG_LOAD(R0, 0); HG_LOAD(R1, 1); HG_LOAD(R2, 2); HG_LOAD(R3, 3); HG_LOAD(R4, 4);
;     HG_STORE(R0, 0); LDSBAR();
;     for (int n = 0; n < nch; n += 6) {
;         HG_LOAD(R5, n + 5); if (active) hg_chunk(ring, S, Ob + (size_t)(n + 0) * 32 * DA, nvalid, vs, lane); if (n + 1 < nch) HG_STORE(R1, 1); LDSBAR(); if (n + 1 >= nch) break;
;         HG_LOAD(R0, n + 6); if (active) hg_chunk(ring + HG_SLOT, S, Ob + (size_t)(n + 1) * 32 * DA, nvalid, vs, lane); if (n + 2 < nch) HG_STORE(R2, 0); LDSBAR(); if (n + 2 >= nch) break;
;         HG_LOAD(R1, n + 7); if (active) hg_chunk(ring, S, Ob + (size_t)(n + 2) * 32 * DA, nvalid, vs, lane); if (n + 3 < nch) HG_STORE(R3, 1); LDSBAR(); if (n + 3 >= nch) break;
;         HG_LOAD(R2, n + 8); if (active) hg_chunk(ring + HG_SLOT, S, Ob + (size_t)(n + 3) * 32 * DA, nvalid, vs, lane); if (n + 4 < nch) HG_STORE(R4, 0); LDSBAR(); if (n + 4 >= nch) break;
;         HG_LOAD(R3, n + 9); if (active) hg_chunk(ring, S, Ob + (size_t)(n + 4) * 32 * DA, nvalid, vs, lane); if (n + 5 < nch) HG_STORE(R5, 1); LDSBAR(); if (n + 5 >= nch) break;
;         HG_LOAD(R4, n + 10); if (active) hg_chunk(ring + HG_SLOT, S, Ob + (size_t)(n + 5) * 32 * DA, nvalid, vs, lane); if (n + 6 < nch) HG_STORE(R0, 0); LDSBAR();
;     }
.Lscan_noadv_527:
	s_add_i32 s60, s60, 21504
	s_cmp_lt_u32 s60, 129024
	s_cselect_b32 s60, s60, 0
	s_waitcnt vmcnt(16)
	s_barrier
.Lscan_ld_loop:
	s_add_i32 m0, s60, s46
	s_nop 0
	global_load_lds_dwordx4 v[8:9], off
	s_add_i32 m0, s60, s47
	s_nop 0
	global_load_lds_dwordx4 v[10:11], off
	s_add_i32 m0, s60, s48
	s_nop 0
	global_load_lds_dwordx4 v[12:13], off
	s_add_i32 m0, s60, s49
	s_nop 0
	global_load_lds_dwordx4 v[14:15], off
	s_cmp_lt_u32 s61, 63
	s_cbranch_scc0 .Lscan_noadv_553
	v_lshl_add_u64 v[8:9], v[8:9], 0, s[52:53]
	v_lshl_add_u64 v[10:11], v[10:11], 0, s[54:55]
	v_lshl_add_u64 v[12:13], v[12:13], 0, s[56:57]
	v_lshl_add_u64 v[14:15], v[14:15], 0, s[58:59]
	s_add_i32 s61, s61, 1
.Lscan_noadv_553:
	s_add_i32 s60, s60, 21504
	s_cmp_lt_u32 s60, 129024
	s_cselect_b32 s60, s60, 0
	s_add_i32 s62, s62, 1
	s_waitcnt vmcnt(16)
	s_barrier
	s_cmp_lt_u32 s62, 64
	s_cbranch_scc1 .Lscan_ld_loop
	s_waitcnt vmcnt(0)
.Lscan_join:
.LBB0_1245:
	s_waitcnt lgkmcnt(0)
	s_barrier

; #define PG8_LAS __attribute__((address_space(3)))
;     __device__ __forceinline__ Pre pre4(int row, int col) const { const float* sb = (row < TP) ? srcP : srcS - (size_t)TP * DM; Pre p; p.s = NTL((const f32x4*)(sb + (size_t)row * DM + col)); return p; }
;     __device__ __forceinline__ Pre pre4(int row, int col) const { const size_t o = (size_t)row * DM + col; Pre p; p.g = NTL((const v2u*)(SG + o)); p.m = (v2u){0u, 0u}; if (MODE == 1) p.m = NTL((const v2u*)(MG + o)); return p; }
;     __device__ __forceinline__ void operator()(const f32x4 (&acc)[2][2][4][2], const Unit& u, int wr, int wc, int fr, int fq) const {
;         const int row0 = u.pm * BM + wr * 64 + fr, col0 = u.pn * BM + wc * 32 + 4 * fq;
;         PG8_LAS float* ROWSUM = (PG8_LAS float*)(ldsb + ROWSUM_OFF);
;         const bool norm = has_norm();
;         if (norm) { if (threadIdx.x < 256) ROWSUM[threadIdx.x] = 0.f; asm volatile("s_waitcnt lgkmcnt(0)" ::: "memory"); __builtin_amdgcn_s_barrier(); asm volatile("" ::: "memory"); }
;         f32x4 gg[2][2];
; #pragma unroll
;         for (int bj = 0; bj < 2; ++bj)
; #pragma unroll
;             for (int n = 0; n < 2; ++n) gg[bj][n] = norm ? *(const f32x4*)(gain + col0 + bj * HALF + n * 16) : (f32x4){0.f, 0.f, 0.f, 0.f};
; #pragma unroll
;         for (int am = 0; am < 4; ++am) {
;             const int ai = am >> 1, mb = (am & 1) * 2;
;             Pre pv[2][2][2];
; #pragma unroll
;             for (int mm = 0; mm < 2; ++mm)
; #pragma unroll
;                 for (int bj = 0; bj < 2; ++bj)
; #pragma unroll
;                     for (int n = 0; n < 2; ++n) pv[mm][bj][n] = pre4(row0 + ai * HALF + (mb + mm) * 16, col0 + bj * HALF + n * 16);
; #pragma unroll
;             for (int mm = 0; mm < 2; ++mm) { const int m = mb + mm; float ss = 0.f;
; #pragma unroll
;                 for (int bj = 0; bj < 2; ++bj)
; #pragma unroll
;                     for (int n = 0; n < 2; ++n) ss += store4pg(row0 + ai * HALF + m * 16, col0 + bj * HALF + n * 16, acc[ai][bj][m][n], pv[mm][bj][n], gg[bj][n]);
.LBB0_1901:
	s_lshl_b32 s100, s64, 20
	s_lshl_b32 s101, s65, 10
	s_add_u32 s98, s20, s100
	s_addc_u32 s99, s21, 0
	s_add_u32 s98, s98, s101
	s_addc_u32 s99, s99, 0
	v_lshlrev_b32_e32 v142, 12, v144
	v_lshl_add_u32 v142, v146, 2, v142
	v_mov_b32_e32 v143, v142
	global_load_dwordx4 v[170:173], v143, s[98:99]
	global_load_dwordx4 v[174:177], v143, s[98:99] offset:64
	global_load_dwordx4 v[178:181], v143, s[98:99] offset:512
	global_load_dwordx4 v[182:185], v143, s[98:99] offset:576
	v_add_u32_e32 v143, 0x10000, v142
	global_load_dwordx4 v[186:189], v143, s[98:99]
	global_load_dwordx4 v[190:193], v143, s[98:99] offset:64
	global_load_dwordx4 v[194:197], v143, s[98:99] offset:512
	global_load_dwordx4 v[198:201], v143, s[98:99] offset:576
	v_add_u32_e32 v143, 0x20000, v142
	global_load_dwordx4 v[202:205], v143, s[98:99]
	global_load_dwordx4 v[206:209], v143, s[98:99] offset:64
	global_load_dwordx4 v[210:213], v143, s[98:99] offset:512
	global_load_dwordx4 v[214:217], v143, s[98:99] offset:576
	v_add_u32_e32 v143, 0x30000, v142
	global_load_dwordx4 v[218:221], v143, s[98:99]
	global_load_dwordx4 v[222:225], v143, s[98:99] offset:64
	global_load_dwordx4 v[226:229], v143, s[98:99] offset:512
	global_load_dwordx4 v[230:233], v143, s[98:99] offset:576
	s_waitcnt vmcnt(8)
	v_pk_fma_f32 v[126:127], v[126:127], 0.5, v[170:171] op_sel_hi:[1,0,1]
	v_pk_fma_f32 v[128:129], v[128:129], 0.5, v[172:173] op_sel_hi:[1,0,1]
	v_pk_fma_f32 v[122:123], v[122:123], 0.5, v[174:175] op_sel_hi:[1,0,1]
	v_pk_fma_f32 v[124:125], v[124:125], 0.5, v[176:177] op_sel_hi:[1,0,1]
	v_pk_fma_f32 v[110:111], v[110:111], 0.5, v[178:179] op_sel_hi:[1,0,1]
	v_pk_fma_f32 v[112:113], v[112:113], 0.5, v[180:181] op_sel_hi:[1,0,1]
	v_pk_fma_f32 v[106:107], v[106:107], 0.5, v[182:183] op_sel_hi:[1,0,1]
	v_pk_fma_f32 v[108:109], v[108:109], 0.5, v[184:185] op_sel_hi:[1,0,1]
	v_pk_fma_f32 v[118:119], v[118:119], 0.5, v[186:187] op_sel_hi:[1,0,1]
	v_pk_fma_f32 v[120:121], v[120:121], 0.5, v[188:189] op_sel_hi:[1,0,1]
	v_pk_fma_f32 v[114:115], v[114:115], 0.5, v[190:191] op_sel_hi:[1,0,1]
	v_pk_fma_f32 v[116:117], v[116:117], 0.5, v[192:193] op_sel_hi:[1,0,1]
	v_pk_fma_f32 v[102:103], v[102:103], 0.5, v[194:195] op_sel_hi:[1,0,1]
	v_pk_fma_f32 v[104:105], v[104:105], 0.5, v[196:197] op_sel_hi:[1,0,1]
	v_pk_fma_f32 v[98:99], v[98:99], 0.5, v[198:199] op_sel_hi:[1,0,1]
	v_pk_fma_f32 v[100:101], v[100:101], 0.5, v[200:201] op_sel_hi:[1,0,1]
	v_add_u32_e32 v143, 0x80000, v142
	global_load_dwordx4 v[170:173], v143, s[98:99]
	global_load_dwordx4 v[174:177], v143, s[98:99] offset:64
	global_load_dwordx4 v[178:181], v143, s[98:99] offset:512
	global_load_dwordx4 v[182:185], v143, s[98:99] offset:576
	v_add_u32_e32 v143, 0x90000, v142
	global_load_dwordx4 v[186:189], v143, s[98:99]
	global_load_dwordx4 v[190:193], v143, s[98:99] offset:64
	global_load_dwordx4 v[194:197], v143, s[98:99] offset:512
	global_load_dwordx4 v[198:201], v143, s[98:99] offset:576
	s_waitcnt vmcnt(8)
	v_pk_fma_f32 v[94:95], v[94:95], 0.5, v[202:203] op_sel_hi:[1,0,1]
	v_pk_fma_f32 v[96:97], v[96:97], 0.5, v[204:205] op_sel_hi:[1,0,1]
	v_pk_fma_f32 v[90:91], v[90:91], 0.5, v[206:207] op_sel_hi:[1,0,1]
	v_pk_fma_f32 v[92:93], v[92:93], 0.5, v[208:209] op_sel_hi:[1,0,1]
	v_pk_fma_f32 v[78:79], v[78:79], 0.5, v[210:211] op_sel_hi:[1,0,1]
	v_pk_fma_f32 v[80:81], v[80:81], 0.5, v[212:213] op_sel_hi:[1,0,1]
	v_pk_fma_f32 v[74:75], v[74:75], 0.5, v[214:215] op_sel_hi:[1,0,1]
	v_pk_fma_f32 v[76:77], v[76:77], 0.5, v[216:217] op_sel_hi:[1,0,1]
	v_pk_fma_f32 v[86:87], v[86:87], 0.5, v[218:219] op_sel_hi:[1,0,1]
	v_pk_fma_f32 v[88:89], v[88:89], 0.5, v[220:221] op_sel_hi:[1,0,1]
	v_pk_fma_f32 v[82:83], v[82:83], 0.5, v[222:223] op_sel_hi:[1,0,1]
	v_pk_fma_f32 v[84:85], v[84:85], 0.5, v[224:225] op_sel_hi:[1,0,1]
	v_pk_fma_f32 v[70:71], v[70:71], 0.5, v[226:227] op_sel_hi:[1,0,1]
	v_pk_fma_f32 v[72:73], v[72:73], 0.5, v[228:229] op_sel_hi:[1,0,1]
	v_pk_fma_f32 v[66:67], v[66:67], 0.5, v[230:231] op_sel_hi:[1,0,1]
	v_pk_fma_f32 v[68:69], v[68:69], 0.5, v[232:233] op_sel_hi:[1,0,1]
	v_add_u32_e32 v143, 0xa0000, v142
	global_load_dwordx4 v[202:205], v143, s[98:99]
	global_load_dwordx4 v[206:209], v143, s[98:99] offset:64
	global_load_dwordx4 v[210:213], v143, s[98:99] offset:512
	global_load_dwordx4 v[214:217], v143, s[98:99] offset:576
	v_add_u32_e32 v143, 0xb0000, v142
	global_load_dwordx4 v[218:221], v143, s[98:99]
	global_load_dwordx4 v[222:225], v143, s[98:99] offset:64
	global_load_dwordx4 v[226:229], v143, s[98:99] offset:512
	global_load_dwordx4 v[230:233], v143, s[98:99] offset:576
	s_waitcnt vmcnt(8)
	v_pk_fma_f32 v[62:63], v[62:63], 0.5, v[170:171] op_sel_hi:[1,0,1]
	v_pk_fma_f32 v[64:65], v[64:65], 0.5, v[172:173] op_sel_hi:[1,0,1]
	v_pk_fma_f32 v[58:59], v[58:59], 0.5, v[174:175] op_sel_hi:[1,0,1]
	v_pk_fma_f32 v[60:61], v[60:61], 0.5, v[176:177] op_sel_hi:[1,0,1]
	v_pk_fma_f32 v[46:47], v[46:47], 0.5, v[178:179] op_sel_hi:[1,0,1]
	v_pk_fma_f32 v[48:49], v[48:49], 0.5, v[180:181] op_sel_hi:[1,0,1]
	v_pk_fma_f32 v[42:43], v[42:43], 0.5, v[182:183] op_sel_hi:[1,0,1]
	v_pk_fma_f32 v[44:45], v[44:45], 0.5, v[184:185] op_sel_hi:[1,0,1]
	v_pk_fma_f32 v[54:55], v[54:55], 0.5, v[186:187] op_sel_hi:[1,0,1]
	v_pk_fma_f32 v[56:57], v[56:57], 0.5, v[188:189] op_sel_hi:[1,0,1]
	v_pk_fma_f32 v[50:51], v[50:51], 0.5, v[190:191] op_sel_hi:[1,0,1]
	v_pk_fma_f32 v[52:53], v[52:53], 0.5, v[192:193] op_sel_hi:[1,0,1]
	v_pk_fma_f32 v[38:39], v[38:39], 0.5, v[194:195] op_sel_hi:[1,0,1]
	v_pk_fma_f32 v[40:41], v[40:41], 0.5, v[196:197] op_sel_hi:[1,0,1]
	v_pk_fma_f32 v[34:35], v[34:35], 0.5, v[198:199] op_sel_hi:[1,0,1]
	v_pk_fma_f32 v[36:37], v[36:37], 0.5, v[200:201] op_sel_hi:[1,0,1]
	s_waitcnt vmcnt(0)
;     __device__ __forceinline__ void operator()(const f32x4 (&acc)[2][2][4][2], const Unit& u, int wr, int wc, int fr, int fq) const {
;     ...
;             for (int mm = 0; mm < 2; ++mm) { const int m = mb + mm; float ss = 0.f;
; #pragma unroll
;                 for (int bj = 0; bj < 2; ++bj)
; #pragma unroll
;                     for (int n = 0; n < 2; ++n) ss += store4pg(row0 + ai * HALF + m * 16, col0 + bj * HALF + n * 16, acc[ai][bj][m][n], pv[mm][bj][n], gg[bj][n]);
;                 if (norm) { ss += __shfl_xor(ss, 16); ss += __shfl_xor(ss, 32); if (fq == 0) (void)__hip_atomic_fetch_add(ROWSUM + ai * HALF + wr * 64 + m * 16 + fr, ss, __ATOMIC_RELAXED, __HIP_MEMORY_SCOPE_WORKGROUP); } }
;         }
;         if (norm) { asm volatile("s_waitcnt lgkmcnt(0)" ::: "memory"); __builtin_amdgcn_s_barrier(); asm volatile("" ::: "memory");
;             if (threadIdx.x < 256) PP[(size_t)(u.pm * BM + threadIdx.x) * 4 + u.pn] = ROWSUM[threadIdx.x]; }
; __device__ __forceinline__ void rms_row2_f32(float* xrow0, const float* g, int lane, bool second_valid) {
;     ...
;     for (int j = 0; j < 8; ++j) { v[j] = NTL(xr + 32 * j); s += (v[j].x * v[j].x + v[j].y * v[j].y) + (v[j].z * v[j].z + v[j].w * v[j].w); }
; #pragma unroll
;     for (int o = 1; o < 32; o <<= 1) s += __shfl_xor(s, o);
;     const float rstd = 1.f / sqrtf(s * (1.f / DM) + EPS);
	v_pk_fma_f32 v[30:31], v[30:31], 0.5, v[202:203] op_sel_hi:[1,0,1]
	v_pk_fma_f32 v[32:33], v[32:33], 0.5, v[204:205] op_sel_hi:[1,0,1]
	v_pk_fma_f32 v[26:27], v[26:27], 0.5, v[206:207] op_sel_hi:[1,0,1]
	v_pk_fma_f32 v[28:29], v[28:29], 0.5, v[208:209] op_sel_hi:[1,0,1]
	v_pk_fma_f32 v[18:19], v[18:19], 0.5, v[210:211] op_sel_hi:[1,0,1]
	v_pk_fma_f32 v[20:21], v[20:21], 0.5, v[212:213] op_sel_hi:[1,0,1]
	v_pk_fma_f32 v[10:11], v[10:11], 0.5, v[214:215] op_sel_hi:[1,0,1]
	v_pk_fma_f32 v[12:13], v[12:13], 0.5, v[216:217] op_sel_hi:[1,0,1]
	v_pk_fma_f32 v[22:23], v[22:23], 0.5, v[218:219] op_sel_hi:[1,0,1]
	v_pk_fma_f32 v[24:25], v[24:25], 0.5, v[220:221] op_sel_hi:[1,0,1]
	v_pk_fma_f32 v[14:15], v[14:15], 0.5, v[222:223] op_sel_hi:[1,0,1]
	v_pk_fma_f32 v[16:17], v[16:17], 0.5, v[224:225] op_sel_hi:[1,0,1]
	v_pk_fma_f32 v[6:7], v[6:7], 0.5, v[226:227] op_sel_hi:[1,0,1]
	v_pk_fma_f32 v[8:9], v[8:9], 0.5, v[228:229] op_sel_hi:[1,0,1]
	v_pk_fma_f32 v[2:3], v[2:3], 0.5, v[230:231] op_sel_hi:[1,0,1]
	v_pk_fma_f32 v[4:5], v[4:5], 0.5, v[232:233] op_sel_hi:[1,0,1]
	v_pk_mul_f32 v[178:179], v[126:127], v[126:127]
	v_pk_fma_f32 v[178:179], v[128:129], v[128:129], v[178:179]
	v_pk_fma_f32 v[178:179], v[122:123], v[122:123], v[178:179]
	v_pk_fma_f32 v[178:179], v[124:125], v[124:125], v[178:179]
	v_pk_fma_f32 v[178:179], v[110:111], v[110:111], v[178:179]
	v_pk_fma_f32 v[178:179], v[112:113], v[112:113], v[178:179]
	v_pk_fma_f32 v[178:179], v[106:107], v[106:107], v[178:179]
	v_pk_fma_f32 v[178:179], v[108:109], v[108:109], v[178:179]
	v_add_f32_e32 v170, v178, v179
	v_pk_mul_f32 v[178:179], v[118:119], v[118:119]
	v_pk_fma_f32 v[178:179], v[120:121], v[120:121], v[178:179]
	v_pk_fma_f32 v[178:179], v[114:115], v[114:115], v[178:179]
	v_pk_fma_f32 v[178:179], v[116:117], v[116:117], v[178:179]
	v_pk_fma_f32 v[178:179], v[102:103], v[102:103], v[178:179]
	v_pk_fma_f32 v[178:179], v[104:105], v[104:105], v[178:179]
	v_pk_fma_f32 v[178:179], v[98:99], v[98:99], v[178:179]
	v_pk_fma_f32 v[178:179], v[100:101], v[100:101], v[178:179]
	v_add_f32_e32 v171, v178, v179
	v_pk_mul_f32 v[178:179], v[94:95], v[94:95]
	v_pk_fma_f32 v[178:179], v[96:97], v[96:97], v[178:179]
	v_pk_fma_f32 v[178:179], v[90:91], v[90:91], v[178:179]
	v_pk_fma_f32 v[178:179], v[92:93], v[92:93], v[178:179]
	v_pk_fma_f32 v[178:179], v[78:79], v[78:79], v[178:179]
	v_pk_fma_f32 v[178:179], v[80:81], v[80:81], v[178:179]
	v_pk_fma_f32 v[178:179], v[74:75], v[74:75], v[178:179]
	v_pk_fma_f32 v[178:179], v[76:77], v[76:77], v[178:179]
	v_add_f32_e32 v172, v178, v179
	v_pk_mul_f32 v[178:179], v[86:87], v[86:87]
	v_pk_fma_f32 v[178:179], v[88:89], v[88:89], v[178:179]
	v_pk_fma_f32 v[178:179], v[82:83], v[82:83], v[178:179]
	v_pk_fma_f32 v[178:179], v[84:85], v[84:85], v[178:179]
	v_pk_fma_f32 v[178:179], v[70:71], v[70:71], v[178:179]
	v_pk_fma_f32 v[178:179], v[72:73], v[72:73], v[178:179]
	v_pk_fma_f32 v[178:179], v[66:67], v[66:67], v[178:179]
	v_pk_fma_f32 v[178:179], v[68:69], v[68:69], v[178:179]
	v_add_f32_e32 v173, v178, v179
	v_pk_mul_f32 v[178:179], v[62:63], v[62:63]
	v_pk_fma_f32 v[178:179], v[64:65], v[64:65], v[178:179]
	v_pk_fma_f32 v[178:179], v[58:59], v[58:59], v[178:179]
	v_pk_fma_f32 v[178:179], v[60:61], v[60:61], v[178:179]
	v_pk_fma_f32 v[178:179], v[46:47], v[46:47], v[178:179]
	v_pk_fma_f32 v[178:179], v[48:49], v[48:49], v[178:179]
	v_pk_fma_f32 v[178:179], v[42:43], v[42:43], v[178:179]
	v_pk_fma_f32 v[178:179], v[44:45], v[44:45], v[178:179]
	v_add_f32_e32 v174, v178, v179
	v_pk_mul_f32 v[178:179], v[54:55], v[54:55]
	v_pk_fma_f32 v[178:179], v[56:57], v[56:57], v[178:179]
	v_pk_fma_f32 v[178:179], v[50:51], v[50:51], v[178:179]
	v_pk_fma_f32 v[178:179], v[52:53], v[52:53], v[178:179]
	v_pk_fma_f32 v[178:179], v[38:39], v[38:39], v[178:179]
	v_pk_fma_f32 v[178:179], v[40:41], v[40:41], v[178:179]
	v_pk_fma_f32 v[178:179], v[34:35], v[34:35], v[178:179]
	v_pk_fma_f32 v[178:179], v[36:37], v[36:37], v[178:179]
	v_add_f32_e32 v175, v178, v179
	v_pk_mul_f32 v[178:179], v[30:31], v[30:31]
	v_pk_fma_f32 v[178:179], v[32:33], v[32:33], v[178:179]
	v_pk_fma_f32 v[178:179], v[26:27], v[26:27], v[178:179]
	v_pk_fma_f32 v[178:179], v[28:29], v[28:29], v[178:179]
	v_pk_fma_f32 v[178:179], v[18:19], v[18:19], v[178:179]
	v_pk_fma_f32 v[178:179], v[20:21], v[20:21], v[178:179]
	v_pk_fma_f32 v[178:179], v[10:11], v[10:11], v[178:179]
	v_pk_fma_f32 v[178:179], v[12:13], v[12:13], v[178:179]
	v_add_f32_e32 v176, v178, v179
	v_pk_mul_f32 v[178:179], v[22:23], v[22:23]
	v_pk_fma_f32 v[178:179], v[24:25], v[24:25], v[178:179]
	v_pk_fma_f32 v[178:179], v[14:15], v[14:15], v[178:179]
	v_pk_fma_f32 v[178:179], v[16:17], v[16:17], v[178:179]
	v_pk_fma_f32 v[178:179], v[6:7], v[6:7], v[178:179]
	v_pk_fma_f32 v[178:179], v[8:9], v[8:9], v[178:179]
	v_pk_fma_f32 v[178:179], v[2:3], v[2:3], v[178:179]
	v_pk_fma_f32 v[178:179], v[4:5], v[4:5], v[178:179]
	v_add_f32_e32 v177, v178, v179
	v_and_b32_e32 v183, 0xff, v0
	v_lshlrev_b32_e32 v184, 2, v183
	v_add_u32_e32 v182, 0x20800, v184
	v_mov_b32_e32 v185, 0
	ds_write_b32 v182, v185
	s_waitcnt lgkmcnt(0)
	s_barrier
	v_lshlrev_b32_e32 v185, 2, v144
	v_add_u32_e32 v185, 0x20800, v185
	ds_add_f32 v185, v170
	ds_add_f32 v185, v171 offset:64
	ds_add_f32 v185, v172 offset:128
	ds_add_f32 v185, v173 offset:192
	ds_add_f32 v185, v174 offset:512
	ds_add_f32 v185, v175 offset:576
	ds_add_f32 v185, v176 offset:640
	ds_add_f32 v185, v177 offset:704
	s_waitcnt lgkmcnt(0)
	s_barrier
	ds_read_b32 v185, v182
	s_lshl_b32 s100, s64, 12
	s_lshl_b32 s101, s65, 2
	s_add_i32 s100, s100, s101
	s_add_u32 s98, s22, 0x20000
	s_addc_u32 s99, s23, 0
	s_add_u32 s98, s98, s100
	s_addc_u32 s99, s99, 0
	v_lshlrev_b32_e32 v184, 4, v183
	s_waitcnt lgkmcnt(0)
	global_store_dword v184, v185, s[98:99] sc0 sc1
	s_waitcnt vmcnt(0)
	s_barrier
	s_lshl_b32 s100, s64, 2
	s_add_u32 s98, s22, 0x10000
	s_addc_u32 s99, s23, 0
	s_add_u32 s98, s98, s100
	s_addc_u32 s99, s99, 0
	v_and_b32_e32 v185, 0x3ff, v0
	v_cmp_eq_u32_e32 vcc, 0, v185
	s_and_saveexec_b64 s[100:101], vcc
	s_cbranch_execz .Lp8f_a_arrived
	v_mov_b32_e32 v187, 0
	v_mov_b32_e32 v185, 1
	global_atomic_add v187, v185, s[98:99]
	v_mov_b32_e32 v185, 0
;     __device__ __forceinline__ void operator()(const f32x4 (&acc)[2][2][4][2], const Unit& u, int wr, int wc, int fr, int fq) const {
;     ...
;         if (norm) { asm volatile("s_waitcnt lgkmcnt(0)" ::: "memory"); __builtin_amdgcn_s_barrier(); asm volatile("" ::: "memory");
;             if (threadIdx.x < 256) PP[(size_t)(u.pm * BM + threadIdx.x) * 4 + u.pn] = ROWSUM[threadIdx.x]; }
; __device__ __forceinline__ void rms_row2_f32(float* xrow0, const float* g, int lane, bool second_valid) {
;     ...
;     for (int j = 0; j < 8; ++j) { v[j] = NTL(xr + 32 * j); s += (v[j].x * v[j].x + v[j].y * v[j].y) + (v[j].z * v[j].z + v[j].w * v[j].w); }
; #pragma unroll
;     for (int o = 1; o < 32; o <<= 1) s += __shfl_xor(s, o);
;     const float rstd = 1.f / sqrtf(s * (1.f / DM) + EPS);
; #pragma unroll
;     for (int j = 0; j < 8; ++j) { const f32x4 gg = gr[32 * j]; xr[32 * j] = v[j] * rstd * gg; }
.Lp8f_a_spin:
	global_load_dword v186, v187, s[98:99] sc1
	s_waitcnt vmcnt(0)
	v_cmp_lt_u32_e32 vcc, 3, v186
	s_cbranch_vccnz .Lp8f_a_arrived
	s_sleep 1
	v_add_u32_e32 v185, 1, v185
	v_cmp_gt_u32_e32 vcc, 0x100000, v185
	s_cbranch_vccnz .Lp8f_a_spin
.Lp8f_a_arrived:
	s_or_b64 exec, exec, s[100:101]
	s_barrier
	s_lshl_b32 s100, s64, 12
	s_add_u32 s98, s22, 0x20000
	s_addc_u32 s99, s23, 0
	s_add_u32 s98, s98, s100
	s_addc_u32 s99, s99, 0
	global_load_dwordx4 v[186:189], v184, s[98:99] sc0 sc1
	s_load_dwordx2 s[98:99], s[0:1], 0xa0
	v_mov_b32_e32 v190, 0x358637bd
	v_mov_b32_e32 v191, 0x260
	s_waitcnt vmcnt(0)
	v_add_f32_e32 v186, v186, v187
	v_add_f32_e32 v188, v188, v189
	v_add_f32_e32 v192, v186, v188
	v_fmamk_f32 v192, v192, 0x3a800000, v190
	v_mul_f32_e32 v194, 0x4f800000, v192
	s_mov_b32 s100, 0xf800000
	v_cmp_gt_f32_e32 vcc, s100, v192
	s_nop 1
	v_cndmask_b32_e32 v192, v192, v194, vcc
	v_sqrt_f32_e32 v194, v192
	s_nop 0
	v_add_u32_e32 v195, -1, v194
	v_add_u32_e32 v196, 1, v194
	v_fma_f32 v197, -v195, v194, v192
	v_fma_f32 v198, -v196, v194, v192
	v_cmp_ge_f32_e64 s[100:101], 0, v197
	s_nop 1
	v_cndmask_b32_e64 v194, v194, v195, s[100:101]
	v_cmp_lt_f32_e64 s[100:101], 0, v198
	s_nop 1
	v_cndmask_b32_e64 v194, v194, v196, s[100:101]
	v_mul_f32_e32 v195, 0x37800000, v194
	v_cndmask_b32_e32 v194, v194, v195, vcc
	v_cmp_class_f32_e32 vcc, v192, v191
	s_nop 1
	v_cndmask_b32_e32 v192, v194, v192, vcc
	v_div_scale_f32 v194, s[100:101], v192, v192, 1.0
	v_rcp_f32_e32 v195, v194
	v_div_scale_f32 v196, vcc, 1.0, v192, 1.0
	v_fma_f32 v197, -v194, v195, 1.0
	v_fmac_f32_e32 v195, v197, v195
	v_mul_f32_e32 v197, v196, v195
	v_fma_f32 v198, -v194, v197, v196
	v_fmac_f32_e32 v197, v198, v195
	v_fma_f32 v194, -v194, v197, v196
	v_div_fmas_f32 v194, v194, v195, v197
	v_div_fixup_f32 v194, v194, v192, 1.0
	v_add_u32_e32 v182, 0x800, v182
	ds_write_b32 v182, v194
	s_waitcnt lgkmcnt(0)
	s_barrier
	v_lshlrev_b32_e32 v184, 2, v146
	s_lshl_b32 s100, s65, 10
	v_add_u32_e32 v184, s100, v184
	global_load_dwordx4 v[202:205], v184, s[98:99]
	global_load_dwordx4 v[206:209], v184, s[98:99] offset:64
	global_load_dwordx4 v[210:213], v184, s[98:99] offset:512
	global_load_dwordx4 v[214:217], v184, s[98:99] offset:576
	v_lshlrev_b32_e32 v185, 2, v144
	v_add_u32_e32 v185, 0x21000, v185
	ds_read_b32 v218, v185
	ds_read_b32 v219, v185 offset:64
	ds_read_b32 v220, v185 offset:128
	ds_read_b32 v221, v185 offset:192
	ds_read_b32 v222, v185 offset:512
	ds_read_b32 v223, v185 offset:576
	ds_read_b32 v224, v185 offset:640
	ds_read_b32 v225, v185 offset:704
	s_lshl_b32 s100, s64, 20
	s_lshl_b32 s101, s65, 10
	s_add_u32 s98, s20, s100
	s_addc_u32 s99, s21, 0
	s_add_u32 s98, s98, s101
	s_addc_u32 s99, s99, 0
	s_waitcnt vmcnt(0) lgkmcnt(0)
	v_mov_b32_e32 v143, v142
	v_mov_b32_e32 v178, v218
	v_pk_mul_f32 v[126:127], v[126:127], v[178:179] op_sel_hi:[1,0]
	v_pk_mul_f32 v[128:129], v[128:129], v[178:179] op_sel_hi:[1,0]
	v_pk_mul_f32 v[126:127], v[202:203], v[126:127]
	v_pk_mul_f32 v[128:129], v[204:205], v[128:129]
	global_store_dwordx4 v143, v[126:129], s[98:99]
	v_pk_mul_f32 v[122:123], v[122:123], v[178:179] op_sel_hi:[1,0]
	v_pk_mul_f32 v[124:125], v[124:125], v[178:179] op_sel_hi:[1,0]
	v_pk_mul_f32 v[122:123], v[206:207], v[122:123]
	v_pk_mul_f32 v[124:125], v[208:209], v[124:125]
	global_store_dwordx4 v143, v[122:125], s[98:99] offset:64
	v_pk_mul_f32 v[110:111], v[110:111], v[178:179] op_sel_hi:[1,0]
	v_pk_mul_f32 v[112:113], v[112:113], v[178:179] op_sel_hi:[1,0]
	v_pk_mul_f32 v[110:111], v[210:211], v[110:111]
	v_pk_mul_f32 v[112:113], v[212:213], v[112:113]
	global_store_dwordx4 v143, v[110:113], s[98:99] offset:512
	v_pk_mul_f32 v[106:107], v[106:107], v[178:179] op_sel_hi:[1,0]
	v_pk_mul_f32 v[108:109], v[108:109], v[178:179] op_sel_hi:[1,0]
	v_pk_mul_f32 v[106:107], v[214:215], v[106:107]
	v_pk_mul_f32 v[108:109], v[216:217], v[108:109]
	global_store_dwordx4 v143, v[106:109], s[98:99] offset:576
	v_add_u32_e32 v143, 0x10000, v142
	v_mov_b32_e32 v178, v219
	v_pk_mul_f32 v[118:119], v[118:119], v[178:179] op_sel_hi:[1,0]
	v_pk_mul_f32 v[120:121], v[120:121], v[178:179] op_sel_hi:[1,0]
	v_pk_mul_f32 v[118:119], v[202:203], v[118:119]
	v_pk_mul_f32 v[120:121], v[204:205], v[120:121]
	global_store_dwordx4 v143, v[118:121], s[98:99]
	v_pk_mul_f32 v[114:115], v[114:115], v[178:179] op_sel_hi:[1,0]
	v_pk_mul_f32 v[116:117], v[116:117], v[178:179] op_sel_hi:[1,0]
	v_pk_mul_f32 v[114:115], v[206:207], v[114:115]
	v_pk_mul_f32 v[116:117], v[208:209], v[116:117]
	global_store_dwordx4 v143, v[114:117], s[98:99] offset:64
	v_pk_mul_f32 v[102:103], v[102:103], v[178:179] op_sel_hi:[1,0]
	v_pk_mul_f32 v[104:105], v[104:105], v[178:179] op_sel_hi:[1,0]
	v_pk_mul_f32 v[102:103], v[210:211], v[102:103]
	v_pk_mul_f32 v[104:105], v[212:213], v[104:105]
	global_store_dwordx4 v143, v[102:105], s[98:99] offset:512
	v_pk_mul_f32 v[98:99], v[98:99], v[178:179] op_sel_hi:[1,0]
	v_pk_mul_f32 v[100:101], v[100:101], v[178:179] op_sel_hi:[1,0]
	v_pk_mul_f32 v[98:99], v[214:215], v[98:99]
	v_pk_mul_f32 v[100:101], v[216:217], v[100:101]
	global_store_dwordx4 v143, v[98:101], s[98:99] offset:576
	v_add_u32_e32 v143, 0x20000, v142
	v_mov_b32_e32 v178, v220
	v_pk_mul_f32 v[94:95], v[94:95], v[178:179] op_sel_hi:[1,0]
	v_pk_mul_f32 v[96:97], v[96:97], v[178:179] op_sel_hi:[1,0]
	v_pk_mul_f32 v[94:95], v[202:203], v[94:95]
	v_pk_mul_f32 v[96:97], v[204:205], v[96:97]
	global_store_dwordx4 v143, v[94:97], s[98:99]
	v_pk_mul_f32 v[90:91], v[90:91], v[178:179] op_sel_hi:[1,0]
	v_pk_mul_f32 v[92:93], v[92:93], v[178:179] op_sel_hi:[1,0]
	v_pk_mul_f32 v[90:91], v[206:207], v[90:91]
; #define GAS __attribute__((address_space(1)))
; __device__ __forceinline__ unsigned pk2(float lo, float hi) { const f32x2_t_ v = {lo, hi}; return __builtin_bit_cast(unsigned, __builtin_convertvector(v, bf16x2_t_)); }
;     __device__ __forceinline__ float store4pg(int row, int col, f32x4 a, const Pre& p, f32x4 gg) const {
;         const size_t o = (size_t)row * DM + col; const f32x4 v = p.s + a * alpha; *(f32x4*)(out + o) = v;
;         if (XNo) { v2u w; w.x = pk2(v[0] * gg[0], v[1] * gg[1]); w.y = pk2(v[2] * gg[2], v[3] * gg[3]); *(v2u*)(XNo + o) = w; return (v[0] * v[0] + v[1] * v[1]) + (v[2] * v[2] + v[3] * v[3]); }
;         return 0.f;
; __device__ __forceinline__ void rms_row2_f32(float* xrow0, const float* g, int lane, bool second_valid) {
;     const int hl = lane & 31, hw = lane >> 5;
;     if (hw && !second_valid) return;
;     GAS f32x4* xr = (GAS f32x4*)(xrow0 + (size_t)hw * DM) + hl; const GAS f32x4* gr = (const GAS f32x4*)g + hl;
;     f32x4 v[8]; float s = 0.f;
; #pragma unroll
;     for (int j = 0; j < 8; ++j) { v[j] = NTL(xr + 32 * j); s += (v[j].x * v[j].x + v[j].y * v[j].y) + (v[j].z * v[j].z + v[j].w * v[j].w); }
; #pragma unroll
;     for (int o = 1; o < 32; o <<= 1) s += __shfl_xor(s, o);
;     const float rstd = 1.f / sqrtf(s * (1.f / DM) + EPS);
; #pragma unroll
;     for (int j = 0; j < 8; ++j) { const f32x4 gg = gr[32 * j]; xr[32 * j] = v[j] * rstd * gg; }
	v_pk_mul_f32 v[92:93], v[208:209], v[92:93]
	global_store_dwordx4 v143, v[90:93], s[98:99] offset:64
	v_pk_mul_f32 v[78:79], v[78:79], v[178:179] op_sel_hi:[1,0]
	v_pk_mul_f32 v[80:81], v[80:81], v[178:179] op_sel_hi:[1,0]
	v_pk_mul_f32 v[78:79], v[210:211], v[78:79]
	v_pk_mul_f32 v[80:81], v[212:213], v[80:81]
	global_store_dwordx4 v143, v[78:81], s[98:99] offset:512
	v_pk_mul_f32 v[74:75], v[74:75], v[178:179] op_sel_hi:[1,0]
	v_pk_mul_f32 v[76:77], v[76:77], v[178:179] op_sel_hi:[1,0]
	v_pk_mul_f32 v[74:75], v[214:215], v[74:75]
	v_pk_mul_f32 v[76:77], v[216:217], v[76:77]
	global_store_dwordx4 v143, v[74:77], s[98:99] offset:576
	v_add_u32_e32 v143, 0x30000, v142
	v_mov_b32_e32 v178, v221
	v_pk_mul_f32 v[86:87], v[86:87], v[178:179] op_sel_hi:[1,0]
	v_pk_mul_f32 v[88:89], v[88:89], v[178:179] op_sel_hi:[1,0]
	v_pk_mul_f32 v[86:87], v[202:203], v[86:87]
	v_pk_mul_f32 v[88:89], v[204:205], v[88:89]
	global_store_dwordx4 v143, v[86:89], s[98:99]
	v_pk_mul_f32 v[82:83], v[82:83], v[178:179] op_sel_hi:[1,0]
	v_pk_mul_f32 v[84:85], v[84:85], v[178:179] op_sel_hi:[1,0]
	v_pk_mul_f32 v[82:83], v[206:207], v[82:83]
	v_pk_mul_f32 v[84:85], v[208:209], v[84:85]
	global_store_dwordx4 v143, v[82:85], s[98:99] offset:64
	v_pk_mul_f32 v[70:71], v[70:71], v[178:179] op_sel_hi:[1,0]
	v_pk_mul_f32 v[72:73], v[72:73], v[178:179] op_sel_hi:[1,0]
	v_pk_mul_f32 v[70:71], v[210:211], v[70:71]
	v_pk_mul_f32 v[72:73], v[212:213], v[72:73]
	global_store_dwordx4 v143, v[70:73], s[98:99] offset:512
	v_pk_mul_f32 v[66:67], v[66:67], v[178:179] op_sel_hi:[1,0]
	v_pk_mul_f32 v[68:69], v[68:69], v[178:179] op_sel_hi:[1,0]
	v_pk_mul_f32 v[66:67], v[214:215], v[66:67]
	v_pk_mul_f32 v[68:69], v[216:217], v[68:69]
	global_store_dwordx4 v143, v[66:69], s[98:99] offset:576
	v_add_u32_e32 v143, 0x80000, v142
	v_mov_b32_e32 v178, v222
	v_pk_mul_f32 v[62:63], v[62:63], v[178:179] op_sel_hi:[1,0]
	v_pk_mul_f32 v[64:65], v[64:65], v[178:179] op_sel_hi:[1,0]
	v_pk_mul_f32 v[62:63], v[202:203], v[62:63]
	v_pk_mul_f32 v[64:65], v[204:205], v[64:65]
	global_store_dwordx4 v143, v[62:65], s[98:99]
	v_pk_mul_f32 v[58:59], v[58:59], v[178:179] op_sel_hi:[1,0]
	v_pk_mul_f32 v[60:61], v[60:61], v[178:179] op_sel_hi:[1,0]
	v_pk_mul_f32 v[58:59], v[206:207], v[58:59]
	v_pk_mul_f32 v[60:61], v[208:209], v[60:61]
	global_store_dwordx4 v143, v[58:61], s[98:99] offset:64
	v_pk_mul_f32 v[46:47], v[46:47], v[178:179] op_sel_hi:[1,0]
	v_pk_mul_f32 v[48:49], v[48:49], v[178:179] op_sel_hi:[1,0]
	v_pk_mul_f32 v[46:47], v[210:211], v[46:47]
	v_pk_mul_f32 v[48:49], v[212:213], v[48:49]
	global_store_dwordx4 v143, v[46:49], s[98:99] offset:512
	v_pk_mul_f32 v[42:43], v[42:43], v[178:179] op_sel_hi:[1,0]
	v_pk_mul_f32 v[44:45], v[44:45], v[178:179] op_sel_hi:[1,0]
	v_pk_mul_f32 v[42:43], v[214:215], v[42:43]
	v_pk_mul_f32 v[44:45], v[216:217], v[44:45]
	global_store_dwordx4 v143, v[42:45], s[98:99] offset:576
	v_add_u32_e32 v143, 0x90000, v142
	v_mov_b32_e32 v178, v223
	v_pk_mul_f32 v[54:55], v[54:55], v[178:179] op_sel_hi:[1,0]
	v_pk_mul_f32 v[56:57], v[56:57], v[178:179] op_sel_hi:[1,0]
	v_pk_mul_f32 v[54:55], v[202:203], v[54:55]
	v_pk_mul_f32 v[56:57], v[204:205], v[56:57]
	global_store_dwordx4 v143, v[54:57], s[98:99]
	v_pk_mul_f32 v[50:51], v[50:51], v[178:179] op_sel_hi:[1,0]
	v_pk_mul_f32 v[52:53], v[52:53], v[178:179] op_sel_hi:[1,0]
	v_pk_mul_f32 v[50:51], v[206:207], v[50:51]
	v_pk_mul_f32 v[52:53], v[208:209], v[52:53]
	global_store_dwordx4 v143, v[50:53], s[98:99] offset:64
	v_pk_mul_f32 v[38:39], v[38:39], v[178:179] op_sel_hi:[1,0]
	v_pk_mul_f32 v[40:41], v[40:41], v[178:179] op_sel_hi:[1,0]
	v_pk_mul_f32 v[38:39], v[210:211], v[38:39]
	v_pk_mul_f32 v[40:41], v[212:213], v[40:41]
	global_store_dwordx4 v143, v[38:41], s[98:99] offset:512
	v_pk_mul_f32 v[34:35], v[34:35], v[178:179] op_sel_hi:[1,0]
	v_pk_mul_f32 v[36:37], v[36:37], v[178:179] op_sel_hi:[1,0]
	v_pk_mul_f32 v[34:35], v[214:215], v[34:35]
	v_pk_mul_f32 v[36:37], v[216:217], v[36:37]
	global_store_dwordx4 v143, v[34:37], s[98:99] offset:576
	v_add_u32_e32 v143, 0xa0000, v142
	v_mov_b32_e32 v178, v224
	v_pk_mul_f32 v[30:31], v[30:31], v[178:179] op_sel_hi:[1,0]
	v_pk_mul_f32 v[32:33], v[32:33], v[178:179] op_sel_hi:[1,0]
	v_pk_mul_f32 v[30:31], v[202:203], v[30:31]
	v_pk_mul_f32 v[32:33], v[204:205], v[32:33]
	global_store_dwordx4 v143, v[30:33], s[98:99]
	v_pk_mul_f32 v[26:27], v[26:27], v[178:179] op_sel_hi:[1,0]
	v_pk_mul_f32 v[28:29], v[28:29], v[178:179] op_sel_hi:[1,0]
	v_pk_mul_f32 v[26:27], v[206:207], v[26:27]
	v_pk_mul_f32 v[28:29], v[208:209], v[28:29]
	global_store_dwordx4 v143, v[26:29], s[98:99] offset:64
	v_pk_mul_f32 v[18:19], v[18:19], v[178:179] op_sel_hi:[1,0]
	v_pk_mul_f32 v[20:21], v[20:21], v[178:179] op_sel_hi:[1,0]
	v_pk_mul_f32 v[18:19], v[210:211], v[18:19]
	v_pk_mul_f32 v[20:21], v[212:213], v[20:21]
	global_store_dwordx4 v143, v[18:21], s[98:99] offset:512
	v_pk_mul_f32 v[10:11], v[10:11], v[178:179] op_sel_hi:[1,0]
	v_pk_mul_f32 v[12:13], v[12:13], v[178:179] op_sel_hi:[1,0]
	v_pk_mul_f32 v[10:11], v[214:215], v[10:11]
	v_pk_mul_f32 v[12:13], v[216:217], v[12:13]
	global_store_dwordx4 v143, v[10:13], s[98:99] offset:576
	v_add_u32_e32 v143, 0xb0000, v142
	v_mov_b32_e32 v178, v225
	v_pk_mul_f32 v[22:23], v[22:23], v[178:179] op_sel_hi:[1,0]
	v_pk_mul_f32 v[24:25], v[24:25], v[178:179] op_sel_hi:[1,0]
	v_pk_mul_f32 v[22:23], v[202:203], v[22:23]
	v_pk_mul_f32 v[24:25], v[204:205], v[24:25]
	global_store_dwordx4 v143, v[22:25], s[98:99]
	v_pk_mul_f32 v[14:15], v[14:15], v[178:179] op_sel_hi:[1,0]
	v_pk_mul_f32 v[16:17], v[16:17], v[178:179] op_sel_hi:[1,0]
	v_pk_mul_f32 v[14:15], v[206:207], v[14:15]
	v_pk_mul_f32 v[16:17], v[208:209], v[16:17]
	global_store_dwordx4 v143, v[14:17], s[98:99] offset:64
	v_pk_mul_f32 v[6:7], v[6:7], v[178:179] op_sel_hi:[1,0]
	v_pk_mul_f32 v[8:9], v[8:9], v[178:179] op_sel_hi:[1,0]
	v_pk_mul_f32 v[6:7], v[210:211], v[6:7]
	v_pk_mul_f32 v[8:9], v[212:213], v[8:9]
	global_store_dwordx4 v143, v[6:9], s[98:99] offset:512
	v_pk_mul_f32 v[2:3], v[2:3], v[178:179] op_sel_hi:[1,0]
	v_pk_mul_f32 v[4:5], v[4:5], v[178:179] op_sel_hi:[1,0]
	v_pk_mul_f32 v[2:3], v[214:215], v[2:3]
	v_pk_mul_f32 v[4:5], v[216:217], v[4:5]
	global_store_dwordx4 v143, v[2:5], s[98:99] offset:576
	s_mov_b64 s[42:43], -1
	s_and_b64 vcc, exec, s[6:7]
	s_cbranch_vccnz .LBB0_1886
	s_andn2_b64 vcc, exec, s[14:15]
	s_cbranch_vccnz .LBB0_1885
	s_barrier
	s_branch .LBB0_1885

;     __device__ __forceinline__ Pre pre4(int row, int col) const { const size_t o = (size_t)row * DM + col; Pre p; p.g = NTL((const v2u*)(SG + o)); p.m = (v2u){0u, 0u}; if (MODE == 1) p.m = NTL((const v2u*)(MG + o)); return p; }
;     __device__ __forceinline__ Pre pre4(int row, int col) const { const float* sb = (row < TP) ? srcP : srcS - (size_t)TP * DM; Pre p; p.s = NTL((const f32x4*)(sb + (size_t)row * DM + col)); return p; }
;     __device__ __forceinline__ float store4pg(int row, int col, f32x4 a, const Pre& p, f32x4 gg) const {
;         const size_t o = (size_t)row * DM + col; const f32x4 v = p.s + a * alpha; *(f32x4*)(out + o) = v;
;     __device__ __forceinline__ void operator()(const f32x4 (&acc)[2][2][4][2], const Unit& u, int wr, int wc, int fr, int fq) const {
;     ...
;         for (int am = 0; am < 4; ++am) {
;             const int ai = am >> 1, mb = (am & 1) * 2;
;             Pre pv[2][2][2];
; #pragma unroll
;             for (int mm = 0; mm < 2; ++mm)
; #pragma unroll
;                 for (int bj = 0; bj < 2; ++bj)
; #pragma unroll
;                     for (int n = 0; n < 2; ++n) pv[mm][bj][n] = pre4(row0 + ai * HALF + (mb + mm) * 16, col0 + bj * HALF + n * 16);
; #pragma unroll
;             for (int mm = 0; mm < 2; ++mm) { const int m = mb + mm; float ss = 0.f;
; #pragma unroll
;                 for (int bj = 0; bj < 2; ++bj)
; #pragma unroll
;                     for (int n = 0; n < 2; ++n) ss += store4pg(row0 + ai * HALF + m * 16, col0 + bj * HALF + n * 16, acc[ai][bj][m][n], pv[mm][bj][n], gg[bj][n]);
.LBB0_1931:
	s_lshl_b32 s100, s64, 20
	s_lshl_b32 s101, s65, 10
	s_add_u32 s98, s20, s100
	s_addc_u32 s99, s21, 0
	s_add_u32 s98, s98, s101
	s_addc_u32 s99, s99, 0
	v_lshlrev_b32_e32 v142, 12, v144
	v_lshl_add_u32 v142, v146, 2, v142
	v_mov_b32_e32 v143, v142
	global_load_dwordx4 v[150:153], v143, s[98:99]
	global_load_dwordx4 v[154:157], v143, s[98:99] offset:64
	global_load_dwordx4 v[158:161], v143, s[98:99] offset:512
	global_load_dwordx4 v[162:165], v143, s[98:99] offset:576
	v_add_u32_e32 v143, 0x10000, v142
	global_load_dwordx4 v[166:169], v143, s[98:99]
	global_load_dwordx4 v[170:173], v143, s[98:99] offset:64
	global_load_dwordx4 v[174:177], v143, s[98:99] offset:512
	global_load_dwordx4 v[178:181], v143, s[98:99] offset:576
	v_add_u32_e32 v143, 0x20000, v142
	global_load_dwordx4 v[182:185], v143, s[98:99]
	global_load_dwordx4 v[186:189], v143, s[98:99] offset:64
	global_load_dwordx4 v[190:193], v143, s[98:99] offset:512
	global_load_dwordx4 v[194:197], v143, s[98:99] offset:576
	v_add_u32_e32 v143, 0x30000, v142
	global_load_dwordx4 v[198:201], v143, s[98:99]
	global_load_dwordx4 v[202:205], v143, s[98:99] offset:64
	global_load_dwordx4 v[206:209], v143, s[98:99] offset:512
	global_load_dwordx4 v[210:213], v143, s[98:99] offset:576
	s_waitcnt vmcnt(8)
	v_pk_fma_f32 v[126:127], v[126:127], 0.5, v[150:151] op_sel_hi:[1,0,1]
	v_pk_fma_f32 v[128:129], v[128:129], 0.5, v[152:153] op_sel_hi:[1,0,1]
	v_pk_fma_f32 v[122:123], v[122:123], 0.5, v[154:155] op_sel_hi:[1,0,1]
	v_pk_fma_f32 v[124:125], v[124:125], 0.5, v[156:157] op_sel_hi:[1,0,1]
	v_pk_fma_f32 v[110:111], v[110:111], 0.5, v[158:159] op_sel_hi:[1,0,1]
	v_pk_fma_f32 v[112:113], v[112:113], 0.5, v[160:161] op_sel_hi:[1,0,1]
	v_pk_fma_f32 v[106:107], v[106:107], 0.5, v[162:163] op_sel_hi:[1,0,1]
	v_pk_fma_f32 v[108:109], v[108:109], 0.5, v[164:165] op_sel_hi:[1,0,1]
	v_pk_fma_f32 v[118:119], v[118:119], 0.5, v[166:167] op_sel_hi:[1,0,1]
	v_pk_fma_f32 v[120:121], v[120:121], 0.5, v[168:169] op_sel_hi:[1,0,1]
	v_pk_fma_f32 v[114:115], v[114:115], 0.5, v[170:171] op_sel_hi:[1,0,1]
	v_pk_fma_f32 v[116:117], v[116:117], 0.5, v[172:173] op_sel_hi:[1,0,1]
	v_pk_fma_f32 v[102:103], v[102:103], 0.5, v[174:175] op_sel_hi:[1,0,1]
	v_pk_fma_f32 v[104:105], v[104:105], 0.5, v[176:177] op_sel_hi:[1,0,1]
	v_pk_fma_f32 v[98:99], v[98:99], 0.5, v[178:179] op_sel_hi:[1,0,1]
	v_pk_fma_f32 v[100:101], v[100:101], 0.5, v[180:181] op_sel_hi:[1,0,1]
	v_add_u32_e32 v143, 0x80000, v142
	global_load_dwordx4 v[150:153], v143, s[98:99]
	global_load_dwordx4 v[154:157], v143, s[98:99] offset:64
	global_load_dwordx4 v[158:161], v143, s[98:99] offset:512
	global_load_dwordx4 v[162:165], v143, s[98:99] offset:576
	v_add_u32_e32 v143, 0x90000, v142
	global_load_dwordx4 v[166:169], v143, s[98:99]
	global_load_dwordx4 v[170:173], v143, s[98:99] offset:64
	global_load_dwordx4 v[174:177], v143, s[98:99] offset:512
	global_load_dwordx4 v[178:181], v143, s[98:99] offset:576
	s_waitcnt vmcnt(8)
	v_pk_fma_f32 v[94:95], v[94:95], 0.5, v[182:183] op_sel_hi:[1,0,1]
	v_pk_fma_f32 v[96:97], v[96:97], 0.5, v[184:185] op_sel_hi:[1,0,1]
	v_pk_fma_f32 v[90:91], v[90:91], 0.5, v[186:187] op_sel_hi:[1,0,1]
	v_pk_fma_f32 v[92:93], v[92:93], 0.5, v[188:189] op_sel_hi:[1,0,1]
	v_pk_fma_f32 v[78:79], v[78:79], 0.5, v[190:191] op_sel_hi:[1,0,1]
	v_pk_fma_f32 v[80:81], v[80:81], 0.5, v[192:193] op_sel_hi:[1,0,1]
	v_pk_fma_f32 v[74:75], v[74:75], 0.5, v[194:195] op_sel_hi:[1,0,1]
	v_pk_fma_f32 v[76:77], v[76:77], 0.5, v[196:197] op_sel_hi:[1,0,1]
	v_pk_fma_f32 v[86:87], v[86:87], 0.5, v[198:199] op_sel_hi:[1,0,1]
	v_pk_fma_f32 v[88:89], v[88:89], 0.5, v[200:201] op_sel_hi:[1,0,1]
	v_pk_fma_f32 v[82:83], v[82:83], 0.5, v[202:203] op_sel_hi:[1,0,1]
	v_pk_fma_f32 v[84:85], v[84:85], 0.5, v[204:205] op_sel_hi:[1,0,1]
	v_pk_fma_f32 v[70:71], v[70:71], 0.5, v[206:207] op_sel_hi:[1,0,1]
	v_pk_fma_f32 v[72:73], v[72:73], 0.5, v[208:209] op_sel_hi:[1,0,1]
	v_pk_fma_f32 v[66:67], v[66:67], 0.5, v[210:211] op_sel_hi:[1,0,1]
	v_pk_fma_f32 v[68:69], v[68:69], 0.5, v[212:213] op_sel_hi:[1,0,1]
	v_add_u32_e32 v143, 0xa0000, v142
	global_load_dwordx4 v[182:185], v143, s[98:99]
	global_load_dwordx4 v[186:189], v143, s[98:99] offset:64
	global_load_dwordx4 v[190:193], v143, s[98:99] offset:512
	global_load_dwordx4 v[194:197], v143, s[98:99] offset:576
	v_add_u32_e32 v143, 0xb0000, v142
	global_load_dwordx4 v[198:201], v143, s[98:99]
	global_load_dwordx4 v[202:205], v143, s[98:99] offset:64
	global_load_dwordx4 v[206:209], v143, s[98:99] offset:512
	global_load_dwordx4 v[210:213], v143, s[98:99] offset:576
	s_waitcnt vmcnt(8)
	v_pk_fma_f32 v[62:63], v[62:63], 0.5, v[150:151] op_sel_hi:[1,0,1]
	v_pk_fma_f32 v[64:65], v[64:65], 0.5, v[152:153] op_sel_hi:[1,0,1]
	v_pk_fma_f32 v[58:59], v[58:59], 0.5, v[154:155] op_sel_hi:[1,0,1]
	v_pk_fma_f32 v[60:61], v[60:61], 0.5, v[156:157] op_sel_hi:[1,0,1]
	v_pk_fma_f32 v[46:47], v[46:47], 0.5, v[158:159] op_sel_hi:[1,0,1]
	v_pk_fma_f32 v[48:49], v[48:49], 0.5, v[160:161] op_sel_hi:[1,0,1]
	v_pk_fma_f32 v[42:43], v[42:43], 0.5, v[162:163] op_sel_hi:[1,0,1]
	v_pk_fma_f32 v[44:45], v[44:45], 0.5, v[164:165] op_sel_hi:[1,0,1]
	v_pk_fma_f32 v[54:55], v[54:55], 0.5, v[166:167] op_sel_hi:[1,0,1]
	v_pk_fma_f32 v[56:57], v[56:57], 0.5, v[168:169] op_sel_hi:[1,0,1]
	v_pk_fma_f32 v[50:51], v[50:51], 0.5, v[170:171] op_sel_hi:[1,0,1]
	v_pk_fma_f32 v[52:53], v[52:53], 0.5, v[172:173] op_sel_hi:[1,0,1]
	v_pk_fma_f32 v[38:39], v[38:39], 0.5, v[174:175] op_sel_hi:[1,0,1]
	v_pk_fma_f32 v[40:41], v[40:41], 0.5, v[176:177] op_sel_hi:[1,0,1]
	v_pk_fma_f32 v[34:35], v[34:35], 0.5, v[178:179] op_sel_hi:[1,0,1]
	v_pk_fma_f32 v[36:37], v[36:37], 0.5, v[180:181] op_sel_hi:[1,0,1]
	s_waitcnt vmcnt(0)
;     __device__ __forceinline__ Pre pre4(int row, int col) const { const float* sb = (row < TP) ? srcP : srcS - (size_t)TP * DM; Pre p; p.s = NTL((const f32x4*)(sb + (size_t)row * DM + col)); return p; }
;     __device__ __forceinline__ Pre pre4(int row, int col) const { const size_t o = (size_t)row * DM + col; Pre p; p.g = NTL((const v2u*)(SG + o)); p.m = (v2u){0u, 0u}; if (MODE == 1) p.m = NTL((const v2u*)(MG + o)); return p; }
;     __device__ __forceinline__ void operator()(const f32x4 (&acc)[2][2][4][2], const Unit& u, int wr, int wc, int fr, int fq) const {
;     ...
;         if (norm) { if (threadIdx.x < 256) ROWSUM[threadIdx.x] = 0.f; asm volatile("s_waitcnt lgkmcnt(0)" ::: "memory"); __builtin_amdgcn_s_barrier(); asm volatile("" ::: "memory"); }
;         f32x4 gg[2][2];
; #pragma unroll
;         for (int bj = 0; bj < 2; ++bj)
; #pragma unroll
;             for (int n = 0; n < 2; ++n) gg[bj][n] = norm ? *(const f32x4*)(gain + col0 + bj * HALF + n * 16) : (f32x4){0.f, 0.f, 0.f, 0.f};
; #pragma unroll
;         for (int am = 0; am < 4; ++am) {
;             const int ai = am >> 1, mb = (am & 1) * 2;
;             Pre pv[2][2][2];
; #pragma unroll
;             for (int mm = 0; mm < 2; ++mm)
; #pragma unroll
;                 for (int bj = 0; bj < 2; ++bj)
; #pragma unroll
;                     for (int n = 0; n < 2; ++n) pv[mm][bj][n] = pre4(row0 + ai * HALF + (mb + mm) * 16, col0 + bj * HALF + n * 16);
; #pragma unroll
;             for (int mm = 0; mm < 2; ++mm) { const int m = mb + mm; float ss = 0.f;
; #pragma unroll
;                 for (int bj = 0; bj < 2; ++bj)
; #pragma unroll
;                     for (int n = 0; n < 2; ++n) ss += store4pg(row0 + ai * HALF + m * 16, col0 + bj * HALF + n * 16, acc[ai][bj][m][n], pv[mm][bj][n], gg[bj][n]);
;                 if (norm) { ss += __shfl_xor(ss, 16); ss += __shfl_xor(ss, 32); if (fq == 0) (void)__hip_atomic_fetch_add(ROWSUM + ai * HALF + wr * 64 + m * 16 + fr, ss, __ATOMIC_RELAXED, __HIP_MEMORY_SCOPE_WORKGROUP); } }
;         }
;         if (norm) { asm volatile("s_waitcnt lgkmcnt(0)" ::: "memory"); __builtin_amdgcn_s_barrier(); asm volatile("" ::: "memory");
;             if (threadIdx.x < 256) PP[(size_t)(u.pm * BM + threadIdx.x) * 4 + u.pn] = ROWSUM[threadIdx.x]; }
	v_pk_fma_f32 v[30:31], v[30:31], 0.5, v[182:183] op_sel_hi:[1,0,1]
	v_pk_fma_f32 v[32:33], v[32:33], 0.5, v[184:185] op_sel_hi:[1,0,1]
	v_pk_fma_f32 v[26:27], v[26:27], 0.5, v[186:187] op_sel_hi:[1,0,1]
	v_pk_fma_f32 v[28:29], v[28:29], 0.5, v[188:189] op_sel_hi:[1,0,1]
	v_pk_fma_f32 v[18:19], v[18:19], 0.5, v[190:191] op_sel_hi:[1,0,1]
	v_pk_fma_f32 v[20:21], v[20:21], 0.5, v[192:193] op_sel_hi:[1,0,1]
	v_pk_fma_f32 v[10:11], v[10:11], 0.5, v[194:195] op_sel_hi:[1,0,1]
	v_pk_fma_f32 v[12:13], v[12:13], 0.5, v[196:197] op_sel_hi:[1,0,1]
	v_pk_fma_f32 v[22:23], v[22:23], 0.5, v[198:199] op_sel_hi:[1,0,1]
	v_pk_fma_f32 v[24:25], v[24:25], 0.5, v[200:201] op_sel_hi:[1,0,1]
	v_pk_fma_f32 v[14:15], v[14:15], 0.5, v[202:203] op_sel_hi:[1,0,1]
	v_pk_fma_f32 v[16:17], v[16:17], 0.5, v[204:205] op_sel_hi:[1,0,1]
	v_pk_fma_f32 v[6:7], v[6:7], 0.5, v[206:207] op_sel_hi:[1,0,1]
	v_pk_fma_f32 v[8:9], v[8:9], 0.5, v[208:209] op_sel_hi:[1,0,1]
	v_pk_fma_f32 v[2:3], v[2:3], 0.5, v[210:211] op_sel_hi:[1,0,1]
	v_pk_fma_f32 v[4:5], v[4:5], 0.5, v[212:213] op_sel_hi:[1,0,1]
	v_pk_mul_f32 v[158:159], v[126:127], v[126:127]
	v_pk_fma_f32 v[158:159], v[128:129], v[128:129], v[158:159]
	v_pk_fma_f32 v[158:159], v[122:123], v[122:123], v[158:159]
	v_pk_fma_f32 v[158:159], v[124:125], v[124:125], v[158:159]
	v_pk_fma_f32 v[158:159], v[110:111], v[110:111], v[158:159]
	v_pk_fma_f32 v[158:159], v[112:113], v[112:113], v[158:159]
	v_pk_fma_f32 v[158:159], v[106:107], v[106:107], v[158:159]
	v_pk_fma_f32 v[158:159], v[108:109], v[108:109], v[158:159]
	v_add_f32_e32 v150, v158, v159
	v_pk_mul_f32 v[158:159], v[118:119], v[118:119]
	v_pk_fma_f32 v[158:159], v[120:121], v[120:121], v[158:159]
	v_pk_fma_f32 v[158:159], v[114:115], v[114:115], v[158:159]
	v_pk_fma_f32 v[158:159], v[116:117], v[116:117], v[158:159]
	v_pk_fma_f32 v[158:159], v[102:103], v[102:103], v[158:159]
	v_pk_fma_f32 v[158:159], v[104:105], v[104:105], v[158:159]
	v_pk_fma_f32 v[158:159], v[98:99], v[98:99], v[158:159]
	v_pk_fma_f32 v[158:159], v[100:101], v[100:101], v[158:159]
	v_add_f32_e32 v151, v158, v159
	v_pk_mul_f32 v[158:159], v[94:95], v[94:95]
	v_pk_fma_f32 v[158:159], v[96:97], v[96:97], v[158:159]
	v_pk_fma_f32 v[158:159], v[90:91], v[90:91], v[158:159]
	v_pk_fma_f32 v[158:159], v[92:93], v[92:93], v[158:159]
	v_pk_fma_f32 v[158:159], v[78:79], v[78:79], v[158:159]
	v_pk_fma_f32 v[158:159], v[80:81], v[80:81], v[158:159]
	v_pk_fma_f32 v[158:159], v[74:75], v[74:75], v[158:159]
	v_pk_fma_f32 v[158:159], v[76:77], v[76:77], v[158:159]
	v_add_f32_e32 v152, v158, v159
	v_pk_mul_f32 v[158:159], v[86:87], v[86:87]
	v_pk_fma_f32 v[158:159], v[88:89], v[88:89], v[158:159]
	v_pk_fma_f32 v[158:159], v[82:83], v[82:83], v[158:159]
	v_pk_fma_f32 v[158:159], v[84:85], v[84:85], v[158:159]
	v_pk_fma_f32 v[158:159], v[70:71], v[70:71], v[158:159]
	v_pk_fma_f32 v[158:159], v[72:73], v[72:73], v[158:159]
	v_pk_fma_f32 v[158:159], v[66:67], v[66:67], v[158:159]
	v_pk_fma_f32 v[158:159], v[68:69], v[68:69], v[158:159]
	v_add_f32_e32 v153, v158, v159
	v_pk_mul_f32 v[158:159], v[62:63], v[62:63]
	v_pk_fma_f32 v[158:159], v[64:65], v[64:65], v[158:159]
	v_pk_fma_f32 v[158:159], v[58:59], v[58:59], v[158:159]
	v_pk_fma_f32 v[158:159], v[60:61], v[60:61], v[158:159]
	v_pk_fma_f32 v[158:159], v[46:47], v[46:47], v[158:159]
	v_pk_fma_f32 v[158:159], v[48:49], v[48:49], v[158:159]
	v_pk_fma_f32 v[158:159], v[42:43], v[42:43], v[158:159]
	v_pk_fma_f32 v[158:159], v[44:45], v[44:45], v[158:159]
	v_add_f32_e32 v154, v158, v159
	v_pk_mul_f32 v[158:159], v[54:55], v[54:55]
	v_pk_fma_f32 v[158:159], v[56:57], v[56:57], v[158:159]
	v_pk_fma_f32 v[158:159], v[50:51], v[50:51], v[158:159]
	v_pk_fma_f32 v[158:159], v[52:53], v[52:53], v[158:159]
	v_pk_fma_f32 v[158:159], v[38:39], v[38:39], v[158:159]
	v_pk_fma_f32 v[158:159], v[40:41], v[40:41], v[158:159]
	v_pk_fma_f32 v[158:159], v[34:35], v[34:35], v[158:159]
	v_pk_fma_f32 v[158:159], v[36:37], v[36:37], v[158:159]
	v_add_f32_e32 v155, v158, v159
	v_pk_mul_f32 v[158:159], v[30:31], v[30:31]
	v_pk_fma_f32 v[158:159], v[32:33], v[32:33], v[158:159]
	v_pk_fma_f32 v[158:159], v[26:27], v[26:27], v[158:159]
	v_pk_fma_f32 v[158:159], v[28:29], v[28:29], v[158:159]
	v_pk_fma_f32 v[158:159], v[18:19], v[18:19], v[158:159]
	v_pk_fma_f32 v[158:159], v[20:21], v[20:21], v[158:159]
	v_pk_fma_f32 v[158:159], v[10:11], v[10:11], v[158:159]
	v_pk_fma_f32 v[158:159], v[12:13], v[12:13], v[158:159]
	v_add_f32_e32 v156, v158, v159
	v_pk_mul_f32 v[158:159], v[22:23], v[22:23]
	v_pk_fma_f32 v[158:159], v[24:25], v[24:25], v[158:159]
	v_pk_fma_f32 v[158:159], v[14:15], v[14:15], v[158:159]
	v_pk_fma_f32 v[158:159], v[16:17], v[16:17], v[158:159]
	v_pk_fma_f32 v[158:159], v[6:7], v[6:7], v[158:159]
	v_pk_fma_f32 v[158:159], v[8:9], v[8:9], v[158:159]
	v_pk_fma_f32 v[158:159], v[2:3], v[2:3], v[158:159]
	v_pk_fma_f32 v[158:159], v[4:5], v[4:5], v[158:159]
	v_add_f32_e32 v157, v158, v159
	v_and_b32_e32 v163, 0xff, v0
	v_lshlrev_b32_e32 v164, 2, v163
	v_add_u32_e32 v162, 0x20800, v164
	v_mov_b32_e32 v165, 0
	ds_write_b32 v162, v165
	s_waitcnt lgkmcnt(0)
	s_barrier
	v_lshlrev_b32_e32 v165, 2, v144
	v_add_u32_e32 v165, 0x20800, v165
	ds_add_f32 v165, v150
	ds_add_f32 v165, v151 offset:64
	ds_add_f32 v165, v152 offset:128
	ds_add_f32 v165, v153 offset:192
	ds_add_f32 v165, v154 offset:512
	ds_add_f32 v165, v155 offset:576
	ds_add_f32 v165, v156 offset:640
	ds_add_f32 v165, v157 offset:704
	s_waitcnt lgkmcnt(0)
	s_barrier
	ds_read_b32 v165, v162
	s_lshl_b32 s100, s64, 12
	s_lshl_b32 s101, s65, 2
	s_add_i32 s100, s100, s101
	s_add_u32 s98, s22, 0x20000
	s_addc_u32 s99, s23, 0
	s_add_u32 s98, s98, s100
	s_addc_u32 s99, s99, 0
	v_lshlrev_b32_e32 v164, 4, v163
	s_waitcnt lgkmcnt(0)
	global_store_dword v164, v165, s[98:99] sc0 sc1
	s_waitcnt vmcnt(0)
	s_barrier
	s_lshl_b32 s100, s64, 2
	s_add_u32 s98, s22, 0x10000
	s_addc_u32 s99, s23, 0
	s_add_u32 s98, s98, s100
	s_addc_u32 s99, s99, 0
	v_and_b32_e32 v165, 0x3ff, v0
	v_cmp_eq_u32_e32 vcc, 0, v165
	s_and_saveexec_b64 s[100:101], vcc
	s_cbranch_execz .Lp8f_b_arrived
	v_mov_b32_e32 v167, 0
	v_mov_b32_e32 v165, 1
	global_atomic_add v167, v165, s[98:99]
	v_mov_b32_e32 v165, 0
; #define GAS __attribute__((address_space(1)))
; __device__ __forceinline__ float row_rstd(const float* PP, const float* PS, int row) {
;     float ss;
;     if (row < TP) { const f32x4 a = NTL((const f32x4*)(PP + (size_t)row * 4)); ss = (a[0] + a[1]) + (a[2] + a[3]); }
;     else { const f32x4* p = (const f32x4*)(PS + (size_t)(row - TP) * 16); const f32x4 a = (NTL(p) + NTL(p + 1)) + (NTL(p + 2) + NTL(p + 3)); ss = (a[0] + a[1]) + (a[2] + a[3]); }
;     return 1.0f / sqrtf(ss * (1.0f / DM) + EPS);
; __device__ __forceinline__ void rms_row2_f32(float* xrow0, const float* g, int lane, bool second_valid) {
;     const int hl = lane & 31, hw = lane >> 5;
;     if (hw && !second_valid) return;
;     GAS f32x4* xr = (GAS f32x4*)(xrow0 + (size_t)hw * DM) + hl; const GAS f32x4* gr = (const GAS f32x4*)g + hl;
;     f32x4 v[8]; float s = 0.f;
; #pragma unroll
;     for (int j = 0; j < 8; ++j) { v[j] = NTL(xr + 32 * j); s += (v[j].x * v[j].x + v[j].y * v[j].y) + (v[j].z * v[j].z + v[j].w * v[j].w); }
; #pragma unroll
;     for (int o = 1; o < 32; o <<= 1) s += __shfl_xor(s, o);
;     const float rstd = 1.f / sqrtf(s * (1.f / DM) + EPS);
; #pragma unroll
;     for (int j = 0; j < 8; ++j) { const f32x4 gg = gr[32 * j]; xr[32 * j] = v[j] * rstd * gg; }
.Lp8f_b_spin:
	global_load_dword v166, v167, s[98:99] sc1
	s_waitcnt vmcnt(0)
	v_cmp_lt_u32_e32 vcc, 3, v166
	s_cbranch_vccnz .Lp8f_b_arrived
	s_sleep 1
	v_add_u32_e32 v165, 1, v165
	v_cmp_gt_u32_e32 vcc, 0x100000, v165
	s_cbranch_vccnz .Lp8f_b_spin
.Lp8f_b_arrived:
	s_or_b64 exec, exec, s[100:101]
	s_barrier
	s_lshl_b32 s100, s64, 12
	s_add_u32 s98, s22, 0x20000
	s_addc_u32 s99, s23, 0
	s_add_u32 s98, s98, s100
	s_addc_u32 s99, s99, 0
	global_load_dwordx4 v[166:169], v164, s[98:99] sc0 sc1
	s_load_dwordx2 s[98:99], s[0:1], 0xa0
	v_mov_b32_e32 v170, 0x358637bd
	v_mov_b32_e32 v171, 0x260
	s_waitcnt vmcnt(0)
	v_add_f32_e32 v166, v166, v167
	v_add_f32_e32 v168, v168, v169
	v_add_f32_e32 v172, v166, v168
	v_fmamk_f32 v172, v172, 0x3a800000, v170
	v_mul_f32_e32 v174, 0x4f800000, v172
	s_mov_b32 s100, 0xf800000
	v_cmp_gt_f32_e32 vcc, s100, v172
	s_nop 1
	v_cndmask_b32_e32 v172, v172, v174, vcc
	v_sqrt_f32_e32 v174, v172
	s_nop 0
	v_add_u32_e32 v175, -1, v174
	v_add_u32_e32 v176, 1, v174
	v_fma_f32 v177, -v175, v174, v172
	v_fma_f32 v178, -v176, v174, v172
	v_cmp_ge_f32_e64 s[100:101], 0, v177
	s_nop 1
	v_cndmask_b32_e64 v174, v174, v175, s[100:101]
	v_cmp_lt_f32_e64 s[100:101], 0, v178
	s_nop 1
	v_cndmask_b32_e64 v174, v174, v176, s[100:101]
	v_mul_f32_e32 v175, 0x37800000, v174
	v_cndmask_b32_e32 v174, v174, v175, vcc
	v_cmp_class_f32_e32 vcc, v172, v171
	s_nop 1
	v_cndmask_b32_e32 v172, v174, v172, vcc
	v_div_scale_f32 v174, s[100:101], v172, v172, 1.0
	v_rcp_f32_e32 v175, v174
	v_div_scale_f32 v176, vcc, 1.0, v172, 1.0
	v_fma_f32 v177, -v174, v175, 1.0
	v_fmac_f32_e32 v175, v177, v175
	v_mul_f32_e32 v177, v176, v175
	v_fma_f32 v178, -v174, v177, v176
	v_fmac_f32_e32 v177, v178, v175
	v_fma_f32 v174, -v174, v177, v176
	v_div_fmas_f32 v174, v174, v175, v177
	v_div_fixup_f32 v174, v174, v172, 1.0
	v_add_u32_e32 v162, 0x800, v162
	ds_write_b32 v162, v174
	s_waitcnt lgkmcnt(0)
	s_barrier
	v_lshlrev_b32_e32 v164, 2, v146
	s_lshl_b32 s100, s65, 10
	v_add_u32_e32 v164, s100, v164
	global_load_dwordx4 v[182:185], v164, s[98:99]
	global_load_dwordx4 v[186:189], v164, s[98:99] offset:64
	global_load_dwordx4 v[190:193], v164, s[98:99] offset:512
	global_load_dwordx4 v[194:197], v164, s[98:99] offset:576
	v_lshlrev_b32_e32 v165, 2, v144
	v_add_u32_e32 v165, 0x21000, v165
	ds_read_b32 v198, v165
	ds_read_b32 v199, v165 offset:64
	ds_read_b32 v200, v165 offset:128
	ds_read_b32 v201, v165 offset:192
	ds_read_b32 v202, v165 offset:512
	ds_read_b32 v203, v165 offset:576
	ds_read_b32 v204, v165 offset:640
	ds_read_b32 v205, v165 offset:704
	s_lshl_b32 s100, s64, 20
	s_lshl_b32 s101, s65, 10
	s_add_u32 s98, s20, s100
	s_addc_u32 s99, s21, 0
	s_add_u32 s98, s98, s101
	s_addc_u32 s99, s99, 0
	s_waitcnt vmcnt(0) lgkmcnt(0)
	v_mov_b32_e32 v143, v142
	v_mov_b32_e32 v158, v198
	v_pk_mul_f32 v[126:127], v[126:127], v[158:159] op_sel_hi:[1,0]
	v_pk_mul_f32 v[128:129], v[128:129], v[158:159] op_sel_hi:[1,0]
	v_pk_mul_f32 v[126:127], v[182:183], v[126:127]
	v_pk_mul_f32 v[128:129], v[184:185], v[128:129]
	global_store_dwordx4 v143, v[126:129], s[98:99]
	v_pk_mul_f32 v[122:123], v[122:123], v[158:159] op_sel_hi:[1,0]
	v_pk_mul_f32 v[124:125], v[124:125], v[158:159] op_sel_hi:[1,0]
	v_pk_mul_f32 v[122:123], v[186:187], v[122:123]
	v_pk_mul_f32 v[124:125], v[188:189], v[124:125]
	global_store_dwordx4 v143, v[122:125], s[98:99] offset:64
	v_pk_mul_f32 v[110:111], v[110:111], v[158:159] op_sel_hi:[1,0]
	v_pk_mul_f32 v[112:113], v[112:113], v[158:159] op_sel_hi:[1,0]
	v_pk_mul_f32 v[110:111], v[190:191], v[110:111]
	v_pk_mul_f32 v[112:113], v[192:193], v[112:113]
	global_store_dwordx4 v143, v[110:113], s[98:99] offset:512
	v_pk_mul_f32 v[106:107], v[106:107], v[158:159] op_sel_hi:[1,0]
	v_pk_mul_f32 v[108:109], v[108:109], v[158:159] op_sel_hi:[1,0]
	v_pk_mul_f32 v[106:107], v[194:195], v[106:107]
	v_pk_mul_f32 v[108:109], v[196:197], v[108:109]
	global_store_dwordx4 v143, v[106:109], s[98:99] offset:576
	v_add_u32_e32 v143, 0x10000, v142
	v_mov_b32_e32 v158, v199
	v_pk_mul_f32 v[118:119], v[118:119], v[158:159] op_sel_hi:[1,0]
	v_pk_mul_f32 v[120:121], v[120:121], v[158:159] op_sel_hi:[1,0]
	v_pk_mul_f32 v[118:119], v[182:183], v[118:119]
	v_pk_mul_f32 v[120:121], v[184:185], v[120:121]
	global_store_dwordx4 v143, v[118:121], s[98:99]
	v_pk_mul_f32 v[114:115], v[114:115], v[158:159] op_sel_hi:[1,0]
	v_pk_mul_f32 v[116:117], v[116:117], v[158:159] op_sel_hi:[1,0]
	v_pk_mul_f32 v[114:115], v[186:187], v[114:115]
	v_pk_mul_f32 v[116:117], v[188:189], v[116:117]
	global_store_dwordx4 v143, v[114:117], s[98:99] offset:64
	v_pk_mul_f32 v[102:103], v[102:103], v[158:159] op_sel_hi:[1,0]
	v_pk_mul_f32 v[104:105], v[104:105], v[158:159] op_sel_hi:[1,0]
	v_pk_mul_f32 v[102:103], v[190:191], v[102:103]
	v_pk_mul_f32 v[104:105], v[192:193], v[104:105]
	global_store_dwordx4 v143, v[102:105], s[98:99] offset:512
	v_pk_mul_f32 v[98:99], v[98:99], v[158:159] op_sel_hi:[1,0]
	v_pk_mul_f32 v[100:101], v[100:101], v[158:159] op_sel_hi:[1,0]
	v_pk_mul_f32 v[98:99], v[194:195], v[98:99]
	v_pk_mul_f32 v[100:101], v[196:197], v[100:101]
	global_store_dwordx4 v143, v[98:101], s[98:99] offset:576
	v_add_u32_e32 v143, 0x20000, v142
	v_mov_b32_e32 v158, v200
	v_pk_mul_f32 v[94:95], v[94:95], v[158:159] op_sel_hi:[1,0]
	v_pk_mul_f32 v[96:97], v[96:97], v[158:159] op_sel_hi:[1,0]
	v_pk_mul_f32 v[94:95], v[182:183], v[94:95]
	v_pk_mul_f32 v[96:97], v[184:185], v[96:97]
	global_store_dwordx4 v143, v[94:97], s[98:99]
	v_pk_mul_f32 v[90:91], v[90:91], v[158:159] op_sel_hi:[1,0]
	v_pk_mul_f32 v[92:93], v[92:93], v[158:159] op_sel_hi:[1,0]
	v_pk_mul_f32 v[90:91], v[186:187], v[90:91]
; #define GAS __attribute__((address_space(1)))
; __device__ __forceinline__ unsigned pk2(float lo, float hi) { const f32x2_t_ v = {lo, hi}; return __builtin_bit_cast(unsigned, __builtin_convertvector(v, bf16x2_t_)); }
;     __device__ __forceinline__ float store4pg(int row, int col, f32x4 a, const Pre& p, f32x4 gg) const {
;         const size_t o = (size_t)row * DM + col; const f32x4 v = p.s + a * alpha; *(f32x4*)(out + o) = v;
;         if (XNo) { v2u w; w.x = pk2(v[0] * gg[0], v[1] * gg[1]); w.y = pk2(v[2] * gg[2], v[3] * gg[3]); *(v2u*)(XNo + o) = w; return (v[0] * v[0] + v[1] * v[1]) + (v[2] * v[2] + v[3] * v[3]); }
;         return 0.f;
; __device__ __forceinline__ void rms_row2_f32(float* xrow0, const float* g, int lane, bool second_valid) {
;     const int hl = lane & 31, hw = lane >> 5;
;     if (hw && !second_valid) return;
;     GAS f32x4* xr = (GAS f32x4*)(xrow0 + (size_t)hw * DM) + hl; const GAS f32x4* gr = (const GAS f32x4*)g + hl;
;     f32x4 v[8]; float s = 0.f;
; #pragma unroll
;     for (int j = 0; j < 8; ++j) { v[j] = NTL(xr + 32 * j); s += (v[j].x * v[j].x + v[j].y * v[j].y) + (v[j].z * v[j].z + v[j].w * v[j].w); }
; #pragma unroll
;     for (int o = 1; o < 32; o <<= 1) s += __shfl_xor(s, o);
;     const float rstd = 1.f / sqrtf(s * (1.f / DM) + EPS);
; #pragma unroll
;     for (int j = 0; j < 8; ++j) { const f32x4 gg = gr[32 * j]; xr[32 * j] = v[j] * rstd * gg; }
	v_pk_mul_f32 v[92:93], v[188:189], v[92:93]
	global_store_dwordx4 v143, v[90:93], s[98:99] offset:64
	v_pk_mul_f32 v[78:79], v[78:79], v[158:159] op_sel_hi:[1,0]
	v_pk_mul_f32 v[80:81], v[80:81], v[158:159] op_sel_hi:[1,0]
	v_pk_mul_f32 v[78:79], v[190:191], v[78:79]
	v_pk_mul_f32 v[80:81], v[192:193], v[80:81]
	global_store_dwordx4 v143, v[78:81], s[98:99] offset:512
	v_pk_mul_f32 v[74:75], v[74:75], v[158:159] op_sel_hi:[1,0]
	v_pk_mul_f32 v[76:77], v[76:77], v[158:159] op_sel_hi:[1,0]
	v_pk_mul_f32 v[74:75], v[194:195], v[74:75]
	v_pk_mul_f32 v[76:77], v[196:197], v[76:77]
	global_store_dwordx4 v143, v[74:77], s[98:99] offset:576
	v_add_u32_e32 v143, 0x30000, v142
	v_mov_b32_e32 v158, v201
	v_pk_mul_f32 v[86:87], v[86:87], v[158:159] op_sel_hi:[1,0]
	v_pk_mul_f32 v[88:89], v[88:89], v[158:159] op_sel_hi:[1,0]
	v_pk_mul_f32 v[86:87], v[182:183], v[86:87]
	v_pk_mul_f32 v[88:89], v[184:185], v[88:89]
	global_store_dwordx4 v143, v[86:89], s[98:99]
	v_pk_mul_f32 v[82:83], v[82:83], v[158:159] op_sel_hi:[1,0]
	v_pk_mul_f32 v[84:85], v[84:85], v[158:159] op_sel_hi:[1,0]
	v_pk_mul_f32 v[82:83], v[186:187], v[82:83]
	v_pk_mul_f32 v[84:85], v[188:189], v[84:85]
	global_store_dwordx4 v143, v[82:85], s[98:99] offset:64
	v_pk_mul_f32 v[70:71], v[70:71], v[158:159] op_sel_hi:[1,0]
	v_pk_mul_f32 v[72:73], v[72:73], v[158:159] op_sel_hi:[1,0]
	v_pk_mul_f32 v[70:71], v[190:191], v[70:71]
	v_pk_mul_f32 v[72:73], v[192:193], v[72:73]
	global_store_dwordx4 v143, v[70:73], s[98:99] offset:512
	v_pk_mul_f32 v[66:67], v[66:67], v[158:159] op_sel_hi:[1,0]
	v_pk_mul_f32 v[68:69], v[68:69], v[158:159] op_sel_hi:[1,0]
	v_pk_mul_f32 v[66:67], v[194:195], v[66:67]
	v_pk_mul_f32 v[68:69], v[196:197], v[68:69]
	global_store_dwordx4 v143, v[66:69], s[98:99] offset:576
	v_add_u32_e32 v143, 0x80000, v142
	v_mov_b32_e32 v158, v202
	v_pk_mul_f32 v[62:63], v[62:63], v[158:159] op_sel_hi:[1,0]
	v_pk_mul_f32 v[64:65], v[64:65], v[158:159] op_sel_hi:[1,0]
	v_pk_mul_f32 v[62:63], v[182:183], v[62:63]
	v_pk_mul_f32 v[64:65], v[184:185], v[64:65]
	global_store_dwordx4 v143, v[62:65], s[98:99]
	v_pk_mul_f32 v[58:59], v[58:59], v[158:159] op_sel_hi:[1,0]
	v_pk_mul_f32 v[60:61], v[60:61], v[158:159] op_sel_hi:[1,0]
	v_pk_mul_f32 v[58:59], v[186:187], v[58:59]
	v_pk_mul_f32 v[60:61], v[188:189], v[60:61]
	global_store_dwordx4 v143, v[58:61], s[98:99] offset:64
	v_pk_mul_f32 v[46:47], v[46:47], v[158:159] op_sel_hi:[1,0]
	v_pk_mul_f32 v[48:49], v[48:49], v[158:159] op_sel_hi:[1,0]
	v_pk_mul_f32 v[46:47], v[190:191], v[46:47]
	v_pk_mul_f32 v[48:49], v[192:193], v[48:49]
	global_store_dwordx4 v143, v[46:49], s[98:99] offset:512
	v_pk_mul_f32 v[42:43], v[42:43], v[158:159] op_sel_hi:[1,0]
	v_pk_mul_f32 v[44:45], v[44:45], v[158:159] op_sel_hi:[1,0]
	v_pk_mul_f32 v[42:43], v[194:195], v[42:43]
	v_pk_mul_f32 v[44:45], v[196:197], v[44:45]
	global_store_dwordx4 v143, v[42:45], s[98:99] offset:576
	v_add_u32_e32 v143, 0x90000, v142
	v_mov_b32_e32 v158, v203
	v_pk_mul_f32 v[54:55], v[54:55], v[158:159] op_sel_hi:[1,0]
	v_pk_mul_f32 v[56:57], v[56:57], v[158:159] op_sel_hi:[1,0]
	v_pk_mul_f32 v[54:55], v[182:183], v[54:55]
	v_pk_mul_f32 v[56:57], v[184:185], v[56:57]
	global_store_dwordx4 v143, v[54:57], s[98:99]
	v_pk_mul_f32 v[50:51], v[50:51], v[158:159] op_sel_hi:[1,0]
	v_pk_mul_f32 v[52:53], v[52:53], v[158:159] op_sel_hi:[1,0]
	v_pk_mul_f32 v[50:51], v[186:187], v[50:51]
	v_pk_mul_f32 v[52:53], v[188:189], v[52:53]
	global_store_dwordx4 v143, v[50:53], s[98:99] offset:64
	v_pk_mul_f32 v[38:39], v[38:39], v[158:159] op_sel_hi:[1,0]
	v_pk_mul_f32 v[40:41], v[40:41], v[158:159] op_sel_hi:[1,0]
	v_pk_mul_f32 v[38:39], v[190:191], v[38:39]
	v_pk_mul_f32 v[40:41], v[192:193], v[40:41]
	global_store_dwordx4 v143, v[38:41], s[98:99] offset:512
	v_pk_mul_f32 v[34:35], v[34:35], v[158:159] op_sel_hi:[1,0]
	v_pk_mul_f32 v[36:37], v[36:37], v[158:159] op_sel_hi:[1,0]
	v_pk_mul_f32 v[34:35], v[194:195], v[34:35]
	v_pk_mul_f32 v[36:37], v[196:197], v[36:37]
	global_store_dwordx4 v143, v[34:37], s[98:99] offset:576
	v_add_u32_e32 v143, 0xa0000, v142
	v_mov_b32_e32 v158, v204
	v_pk_mul_f32 v[30:31], v[30:31], v[158:159] op_sel_hi:[1,0]
	v_pk_mul_f32 v[32:33], v[32:33], v[158:159] op_sel_hi:[1,0]
	v_pk_mul_f32 v[30:31], v[182:183], v[30:31]
	v_pk_mul_f32 v[32:33], v[184:185], v[32:33]
	global_store_dwordx4 v143, v[30:33], s[98:99]
	v_pk_mul_f32 v[26:27], v[26:27], v[158:159] op_sel_hi:[1,0]
	v_pk_mul_f32 v[28:29], v[28:29], v[158:159] op_sel_hi:[1,0]
	v_pk_mul_f32 v[26:27], v[186:187], v[26:27]
	v_pk_mul_f32 v[28:29], v[188:189], v[28:29]
	global_store_dwordx4 v143, v[26:29], s[98:99] offset:64
	v_pk_mul_f32 v[18:19], v[18:19], v[158:159] op_sel_hi:[1,0]
	v_pk_mul_f32 v[20:21], v[20:21], v[158:159] op_sel_hi:[1,0]
	v_pk_mul_f32 v[18:19], v[190:191], v[18:19]
	v_pk_mul_f32 v[20:21], v[192:193], v[20:21]
	global_store_dwordx4 v143, v[18:21], s[98:99] offset:512
	v_pk_mul_f32 v[10:11], v[10:11], v[158:159] op_sel_hi:[1,0]
	v_pk_mul_f32 v[12:13], v[12:13], v[158:159] op_sel_hi:[1,0]
	v_pk_mul_f32 v[10:11], v[194:195], v[10:11]
	v_pk_mul_f32 v[12:13], v[196:197], v[12:13]
	global_store_dwordx4 v143, v[10:13], s[98:99] offset:576
	v_add_u32_e32 v143, 0xb0000, v142
	v_mov_b32_e32 v158, v205
	v_pk_mul_f32 v[22:23], v[22:23], v[158:159] op_sel_hi:[1,0]
	v_pk_mul_f32 v[24:25], v[24:25], v[158:159] op_sel_hi:[1,0]
	v_pk_mul_f32 v[22:23], v[182:183], v[22:23]
	v_pk_mul_f32 v[24:25], v[184:185], v[24:25]
	global_store_dwordx4 v143, v[22:25], s[98:99]
	v_pk_mul_f32 v[14:15], v[14:15], v[158:159] op_sel_hi:[1,0]
	v_pk_mul_f32 v[16:17], v[16:17], v[158:159] op_sel_hi:[1,0]
	v_pk_mul_f32 v[14:15], v[186:187], v[14:15]
	v_pk_mul_f32 v[16:17], v[188:189], v[16:17]
	global_store_dwordx4 v143, v[14:17], s[98:99] offset:64
	v_pk_mul_f32 v[6:7], v[6:7], v[158:159] op_sel_hi:[1,0]
	v_pk_mul_f32 v[8:9], v[8:9], v[158:159] op_sel_hi:[1,0]
	v_pk_mul_f32 v[6:7], v[190:191], v[6:7]
	v_pk_mul_f32 v[8:9], v[192:193], v[8:9]
	global_store_dwordx4 v143, v[6:9], s[98:99] offset:512
	v_pk_mul_f32 v[2:3], v[2:3], v[158:159] op_sel_hi:[1,0]
	v_pk_mul_f32 v[4:5], v[4:5], v[158:159] op_sel_hi:[1,0]
	v_pk_mul_f32 v[2:3], v[194:195], v[2:3]
	v_pk_mul_f32 v[4:5], v[196:197], v[4:5]
	global_store_dwordx4 v143, v[2:5], s[98:99] offset:576
	s_mov_b64 s[42:43], -1
	s_and_b64 vcc, exec, s[6:7]
	s_cbranch_vccnz .LBB0_1916
	s_andn2_b64 vcc, exec, s[14:15]
	s_cbranch_vccnz .LBB0_1915
	s_barrier
	s_branch .LBB0_1915

; #define GAS __attribute__((address_space(1)))
; __device__ __forceinline__ const float* kin(int k) { KArgs p = (KArgs)__builtin_amdgcn_kernarg_segment_ptr(); asm volatile("" : "+s"(p)); return p->in[k]; }
; __device__ __forceinline__ void rms_row2_f32(float* xrow0, const float* g, int lane, bool second_valid) {
;     const int hl = lane & 31, hw = lane >> 5;
;     if (hw && !second_valid) return;
;     GAS f32x4* xr = (GAS f32x4*)(xrow0 + (size_t)hw * DM) + hl; const GAS f32x4* gr = (const GAS f32x4*)g + hl;
;     f32x4 v[8]; float s = 0.f;
; #pragma unroll
;     for (int j = 0; j < 8; ++j) { v[j] = NTL(xr + 32 * j); s += (v[j].x * v[j].x + v[j].y * v[j].y) + (v[j].z * v[j].z + v[j].w * v[j].w); }
; #pragma unroll
; __global__ void __launch_bounds__(NWAVES * 64, 2) mk_fwd(Args args) {
;     ...
;     if (phmask & (1u << 10)) {
;     { const float* gg_ = kin(20); for (int m = 2 * GW_; m < T; m += 2 * NGW) rms_row2_f32(out + (size_t)m * DM, gg_, F.lane, m + 1 < T); }
;     }
.LBB0_1991:
	s_lshl_b32 s2, s33, 4
	s_lshl_b32 s3, s50, 1
	s_add_i32 s2, s3, s2
	s_addk_i32 s2, 0x4000
	s_cmpk_gt_i32 s2, 0x43ff
	s_cbranch_scc1 .LBB0_1994
	v_mbcnt_lo_u32_b32 v3, -1, 0
	v_mbcnt_hi_u32_b32 v3, -1, v3
	v_and_b32_e32 v4, 64, v3
	v_add_u32_e32 v4, 64, v4
	v_xor_b32_e32 v5, 1, v3
	v_cmp_lt_i32_e32 vcc, v5, v4
	s_load_dwordx2 s[0:1], s[0:1], 0xa0
	v_and_b32_e32 v2, 31, v189
	v_cndmask_b32_e32 v5, v3, v5, vcc
	s_waitcnt vmcnt(4)
	v_lshlrev_b32_e32 v12, 2, v5
	v_xor_b32_e32 v5, 2, v3
	v_cmp_lt_i32_e32 vcc, v5, v4
	v_mov_b32_e32 v1, 0
	v_lshlrev_b32_e32 v0, 7, v189
	v_cndmask_b32_e32 v5, v3, v5, vcc
	v_lshlrev_b32_e32 v13, 2, v5
	v_xor_b32_e32 v5, 4, v3
	v_cmp_lt_i32_e32 vcc, v5, v4
	v_lshlrev_b32_e32 v2, 4, v2
	s_ashr_i32 s3, s2, 31
	v_cndmask_b32_e32 v5, v3, v5, vcc
	v_lshlrev_b32_e32 v14, 2, v5
	v_xor_b32_e32 v5, 8, v3
	v_cmp_lt_i32_e32 vcc, v5, v4
	v_and_b32_e32 v0, 0x1000, v0
	s_lshl_b32 s4, s18, 4
	v_cndmask_b32_e32 v5, v3, v5, vcc
	v_lshlrev_b32_e32 v15, 2, v5
	v_xor_b32_e32 v5, 16, v3
	v_cmp_lt_i32_e32 vcc, v5, v4
	s_ashr_i32 s5, s4, 31
	s_lshl_b64 s[6:7], s[4:5], 12
	v_cndmask_b32_e32 v3, v3, v5, vcc
	v_lshlrev_b32_e32 v16, 2, v3
	v_mov_b32_e32 v3, v1
	s_waitcnt lgkmcnt(0)
	v_lshl_add_u64 v[8:9], s[0:1], 0, v[2:3]
	s_lshl_b64 s[0:1], s[2:3], 12
	v_lshl_add_u64 v[0:1], v[0:1], 0, s[0:1]
	v_or_b32_e32 v0, v0, v2
	v_lshl_add_u64 v[10:11], s[20:21], 0, v[0:1]
	v_mov_b32_e32 v17, 0x358637bd
	s_mov_b32 s3, 0xf800000
	v_mov_b32_e32 v18, 0x260
	global_load_dwordx4 v[20:23], v[8:9], off offset:0
	global_load_dwordx4 v[24:27], v[8:9], off offset:512
	global_load_dwordx4 v[28:31], v[8:9], off offset:1024
	global_load_dwordx4 v[32:35], v[8:9], off offset:1536
	global_load_dwordx4 v[36:39], v[8:9], off offset:2048
	global_load_dwordx4 v[40:43], v[8:9], off offset:2560
	global_load_dwordx4 v[44:47], v[8:9], off offset:3072
	global_load_dwordx4 v[48:51], v[8:9], off offset:3584

; __global__ void __launch_bounds__(NWAVES * 64, 2) mk_fwd(Args args) {
	.amdhsa_kernel _Z6mk_fwd4Args
		.amdhsa_group_segment_fixed_size 0
		.amdhsa_private_segment_fixed_size 0
		.amdhsa_kernarg_size 448
		.amdhsa_user_sgpr_count 2
		.amdhsa_user_sgpr_dispatch_ptr 0
		.amdhsa_user_sgpr_queue_ptr 0
		.amdhsa_user_sgpr_kernarg_segment_ptr 1
		.amdhsa_user_sgpr_dispatch_id 0
		.amdhsa_user_sgpr_kernarg_preload_length 0
		.amdhsa_user_sgpr_kernarg_preload_offset 0
		.amdhsa_user_sgpr_private_segment_size 0
		.amdhsa_uses_dynamic_stack 0
		.amdhsa_enable_private_segment 0
		.amdhsa_system_sgpr_workgroup_id_x 1
		.amdhsa_system_sgpr_workgroup_id_y 0
		.amdhsa_system_sgpr_workgroup_id_z 0
		.amdhsa_system_sgpr_workgroup_info 0
		.amdhsa_system_vgpr_workitem_id 0
		.amdhsa_next_free_vgpr 244
		.amdhsa_next_free_sgpr 102
		.amdhsa_accum_offset 244
		.amdhsa_reserve_vcc 1
		.amdhsa_float_round_mode_32 0
		.amdhsa_float_round_mode_16_64 0
		.amdhsa_float_denorm_mode_32 3
		.amdhsa_float_denorm_mode_16_64 3
		.amdhsa_dx10_clamp 1
		.amdhsa_ieee_mode 1
		.amdhsa_fp16_overflow 0
		.amdhsa_tg_split 0
		.amdhsa_exception_fp_ieee_invalid_op 0
		.amdhsa_exception_fp_denorm_src 0
		.amdhsa_exception_fp_ieee_div_zero 0
		.amdhsa_exception_fp_ieee_overflow 0
		.amdhsa_exception_fp_ieee_underflow 0
		.amdhsa_exception_fp_ieee_inexact 0
		.amdhsa_exception_int_div_zero 0
	.end_amdhsa_kernel

; __global__ void __launch_bounds__(NWAVES * 64, 2) mk_fwd(Args args) {
amdhsa.kernels:
  - .agpr_count:     0
    .args:
      - .offset:         0
        .size:           192
        .value_kind:     by_value
      - .offset:         192
        .size:           4
        .value_kind:     hidden_block_count_x
      - .offset:         196
        .size:           4
        .value_kind:     hidden_block_count_y
      - .offset:         200
        .size:           4
        .value_kind:     hidden_block_count_z
      - .offset:         204
        .size:           2
        .value_kind:     hidden_group_size_x
      - .offset:         206
        .size:           2
        .value_kind:     hidden_group_size_y
      - .offset:         208
        .size:           2
        .value_kind:     hidden_group_size_z
      - .offset:         210
        .size:           2
        .value_kind:     hidden_remainder_x
      - .offset:         212
        .size:           2
        .value_kind:     hidden_remainder_y
      - .offset:         214
        .size:           2
        .value_kind:     hidden_remainder_z
      - .offset:         232
        .size:           8
        .value_kind:     hidden_global_offset_x
      - .offset:         240
        .size:           8
        .value_kind:     hidden_global_offset_y
      - .offset:         248
        .size:           8
        .value_kind:     hidden_global_offset_z
      - .offset:         256
        .size:           2
        .value_kind:     hidden_grid_dims
      - .offset:         312
        .size:           4
        .value_kind:     hidden_dynamic_lds_size
    .group_segment_fixed_size: 0
    .kernarg_segment_align: 8
    .kernarg_segment_size: 448
    .language:       OpenCL C
    .language_version:
      - 2
      - 0
    .max_flat_workgroup_size: 512
    .name:           _Z6mk_fwd4Args
    .private_segment_fixed_size: 0
    .sgpr_count:     108
    .sgpr_spill_count: 2
    .symbol:         _Z6mk_fwd4Args.kd
    .uniform_work_group_size: 1
    .uses_dynamic_stack: false
    .vgpr_count:     244
    .vgpr_spill_count: 0
    .wavefront_size: 64
